# v5 + remove the adjacent s_setprio 0/1 pair inside each MFMA block of the 7 GEMM main loops
# speedup vs baseline: 1.0197x; 1.0020x over previous
.LBB0_295:
	ds_read_b128 v[146:149], v155
	ds_read_b128 v[160:163], v155 offset:1024
	ds_read_b128 v[164:167], v155 offset:2048
	ds_read_b128 v[168:171], v155 offset:3072
	ds_read_b128 v[172:175], v156
	ds_read_b128 v[176:179], v156 offset:1024
	ds_read_b128 v[180:183], v156 offset:2048
	ds_read_b128 v[184:187], v156 offset:3072
	s_add_u32 s23, s64, 0xfffc0080
	s_addc_u32 s33, s65, -1
	s_cmp_eq_u32 s92, 12
	s_cselect_b32 s73, s20, s33
	s_cselect_b32 s72, s21, s23
	s_cselect_b32 s71, s19, s91
	s_cselect_b32 s70, s55, s90
	v_lshl_add_u64 v[150:151], s[64:65], 0, v[138:139]
	s_add_i32 m0, s76, 0xc000
	ds_read_b128 v[188:191], v157
	ds_read_b128 v[192:195], v157 offset:1024
	ds_read_b128 v[196:199], v157 offset:2048
	ds_read_b128 v[200:203], v157 offset:3072
	ds_read_b128 v[204:207], v157 offset:4096
	ds_read_b128 v[208:211], v157 offset:5120
	ds_read_b128 v[212:215], v157 offset:6144
	ds_read_b128 v[216:219], v157 offset:7168
	global_load_lds_dwordx4 v[150:151], off
	v_lshl_add_u64 v[150:151], s[64:65], 0, v[140:141]
	s_add_i32 m0, s76, 0xe000
	s_nop 0
	global_load_lds_dwordx4 v[150:151], off
	s_waitcnt vmcnt(8)
	s_waitcnt lgkmcnt(0)
	s_barrier
	s_setprio 1
	s_waitcnt lgkmcnt(0)
	v_mfma_f32_16x16x32_bf16 v[124:127], v[146:149], v[188:191], v[124:127]
	v_mfma_f32_16x16x32_bf16 v[120:123], v[164:167], v[188:191], v[120:123]
	v_mfma_f32_16x16x32_bf16 v[108:111], v[146:149], v[196:199], v[108:111]
	v_mfma_f32_16x16x32_bf16 v[104:107], v[164:167], v[196:199], v[104:107]
	v_mfma_f32_16x16x32_bf16 v[92:95], v[146:149], v[204:207], v[92:95]
	v_mfma_f32_16x16x32_bf16 v[88:91], v[164:167], v[204:207], v[88:91]
	v_mfma_f32_16x16x32_bf16 v[76:79], v[146:149], v[212:215], v[76:79]
	v_mfma_f32_16x16x32_bf16 v[72:75], v[164:167], v[212:215], v[72:75]
	v_mfma_f32_16x16x32_bf16 v[124:127], v[160:163], v[192:195], v[124:127]
	v_mfma_f32_16x16x32_bf16 v[120:123], v[168:171], v[192:195], v[120:123]
	v_mfma_f32_16x16x32_bf16 v[108:111], v[160:163], v[200:203], v[108:111]
	v_mfma_f32_16x16x32_bf16 v[104:107], v[168:171], v[200:203], v[104:107]
	v_mfma_f32_16x16x32_bf16 v[92:95], v[160:163], v[208:211], v[92:95]
	v_mfma_f32_16x16x32_bf16 v[88:91], v[168:171], v[208:211], v[88:91]
	v_mfma_f32_16x16x32_bf16 v[76:79], v[160:163], v[216:219], v[76:79]
	v_mfma_f32_16x16x32_bf16 v[72:75], v[168:171], v[216:219], v[72:75]
	v_mfma_f32_16x16x32_bf16 v[116:119], v[172:175], v[188:191], v[116:119]
	v_mfma_f32_16x16x32_bf16 v[112:115], v[180:183], v[188:191], v[112:115]
	v_mfma_f32_16x16x32_bf16 v[100:103], v[172:175], v[196:199], v[100:103]
	v_mfma_f32_16x16x32_bf16 v[96:99], v[180:183], v[196:199], v[96:99]
	v_mfma_f32_16x16x32_bf16 v[84:87], v[172:175], v[204:207], v[84:87]
	v_mfma_f32_16x16x32_bf16 v[80:83], v[180:183], v[204:207], v[80:83]
	v_mfma_f32_16x16x32_bf16 v[68:71], v[172:175], v[212:215], v[68:71]
	v_mfma_f32_16x16x32_bf16 v[64:67], v[180:183], v[212:215], v[64:67]
	v_mfma_f32_16x16x32_bf16 v[116:119], v[176:179], v[192:195], v[116:119]
	v_mfma_f32_16x16x32_bf16 v[112:115], v[184:187], v[192:195], v[112:115]
	v_mfma_f32_16x16x32_bf16 v[100:103], v[176:179], v[200:203], v[100:103]
	v_mfma_f32_16x16x32_bf16 v[96:99], v[184:187], v[200:203], v[96:99]
	v_mfma_f32_16x16x32_bf16 v[84:87], v[176:179], v[208:211], v[84:87]
	v_mfma_f32_16x16x32_bf16 v[80:83], v[184:187], v[208:211], v[80:83]
	v_mfma_f32_16x16x32_bf16 v[68:71], v[176:179], v[216:219], v[68:71]
	v_mfma_f32_16x16x32_bf16 v[64:67], v[184:187], v[216:219], v[64:67]
	s_setprio 0
	s_barrier
	s_add_i32 s23, s85, s74
	v_lshl_add_u64 v[150:151], s[70:71], 0, v[132:133]
	s_mov_b32 m0, s23
	ds_read_b128 v[188:191], v157 offset:16384
	ds_read_b128 v[192:195], v157 offset:17408
	ds_read_b128 v[196:199], v157 offset:18432
	ds_read_b128 v[200:203], v157 offset:19456
	ds_read_b128 v[204:207], v157 offset:20480
	ds_read_b128 v[208:211], v157 offset:21504
	ds_read_b128 v[212:215], v157 offset:22528
	ds_read_b128 v[216:219], v157 offset:23552
	global_load_lds_dwordx4 v[150:151], off
	s_add_i32 m0, s23, 0x2000
	s_add_u32 s94, s70, 0x40000
	v_lshl_add_u64 v[220:221], s[70:71], 0, v[136:137]
	s_addc_u32 s95, s71, 0
	s_add_i32 s23, s86, s74
	global_load_lds_dwordx4 v[220:221], off
	v_lshl_add_u64 v[222:223], s[94:95], 0, v[132:133]
	s_mov_b32 m0, s23
	v_lshl_add_u64 v[224:225], s[72:73], 0, v[134:135]
	global_load_lds_dwordx4 v[222:223], off
	v_lshl_add_u64 v[222:223], s[94:95], 0, v[136:137]
	s_add_i32 m0, s23, 0x2000
	s_nop 0
	global_load_lds_dwordx4 v[222:223], off
	v_lshl_add_u64 v[222:223], s[72:73], 0, v[130:131]
	s_mov_b32 m0, s76
	s_nop 0
	global_load_lds_dwordx4 v[222:223], off
	s_mov_b32 m0, s77
	s_nop 0
	global_load_lds_dwordx4 v[224:225], off
	s_waitcnt vmcnt(8)
	s_waitcnt lgkmcnt(0)
	s_barrier
	s_setprio 1
	s_waitcnt lgkmcnt(0)
	v_mfma_f32_16x16x32_bf16 v[60:63], v[146:149], v[188:191], v[60:63]
	v_mfma_f32_16x16x32_bf16 v[56:59], v[164:167], v[188:191], v[56:59]
	v_mfma_f32_16x16x32_bf16 v[44:47], v[146:149], v[196:199], v[44:47]
	v_mfma_f32_16x16x32_bf16 v[40:43], v[164:167], v[196:199], v[40:43]
	v_mfma_f32_16x16x32_bf16 v[28:31], v[146:149], v[204:207], v[28:31]
	v_mfma_f32_16x16x32_bf16 v[24:27], v[164:167], v[204:207], v[24:27]
	v_mfma_f32_16x16x32_bf16 v[12:15], v[146:149], v[212:215], v[12:15]
	v_mfma_f32_16x16x32_bf16 v[8:11], v[164:167], v[212:215], v[8:11]
	v_mfma_f32_16x16x32_bf16 v[60:63], v[160:163], v[192:195], v[60:63]
	v_mfma_f32_16x16x32_bf16 v[56:59], v[168:171], v[192:195], v[56:59]
	v_mfma_f32_16x16x32_bf16 v[44:47], v[160:163], v[200:203], v[44:47]
	v_mfma_f32_16x16x32_bf16 v[40:43], v[168:171], v[200:203], v[40:43]
	v_mfma_f32_16x16x32_bf16 v[28:31], v[160:163], v[208:211], v[28:31]
	v_mfma_f32_16x16x32_bf16 v[24:27], v[168:171], v[208:211], v[24:27]
	v_mfma_f32_16x16x32_bf16 v[12:15], v[160:163], v[216:219], v[12:15]
	v_mfma_f32_16x16x32_bf16 v[8:11], v[168:171], v[216:219], v[8:11]
	v_mfma_f32_16x16x32_bf16 v[52:55], v[172:175], v[188:191], v[52:55]
	v_mfma_f32_16x16x32_bf16 v[48:51], v[180:183], v[188:191], v[48:51]
	v_mfma_f32_16x16x32_bf16 v[36:39], v[172:175], v[196:199], v[36:39]
	v_mfma_f32_16x16x32_bf16 v[32:35], v[180:183], v[196:199], v[32:35]
	v_mfma_f32_16x16x32_bf16 v[20:23], v[172:175], v[204:207], v[20:23]
	v_mfma_f32_16x16x32_bf16 v[16:19], v[180:183], v[204:207], v[16:19]
	v_mfma_f32_16x16x32_bf16 v[4:7], v[172:175], v[212:215], v[4:7]
	v_mfma_f32_16x16x32_bf16 v[0:3], v[180:183], v[212:215], v[0:3]
	v_mfma_f32_16x16x32_bf16 v[52:55], v[176:179], v[192:195], v[52:55]
	v_mfma_f32_16x16x32_bf16 v[48:51], v[184:187], v[192:195], v[48:51]
	v_mfma_f32_16x16x32_bf16 v[36:39], v[176:179], v[200:203], v[36:39]
	v_mfma_f32_16x16x32_bf16 v[32:35], v[184:187], v[200:203], v[32:35]
	v_mfma_f32_16x16x32_bf16 v[20:23], v[176:179], v[208:211], v[20:23]
	v_mfma_f32_16x16x32_bf16 v[16:19], v[184:187], v[208:211], v[16:19]
	v_mfma_f32_16x16x32_bf16 v[4:7], v[176:179], v[216:219], v[4:7]
	v_mfma_f32_16x16x32_bf16 v[0:3], v[184:187], v[216:219], v[0:3]
	s_setprio 0
	s_barrier
	s_add_i32 s23, 0, 0x18000
	v_add_u32_e32 v159, s23, v153
	s_add_i32 s33, 0, 0x1c000
	ds_read_b128 v[146:149], v159
	ds_read_b128 v[160:163], v159 offset:1024
	ds_read_b128 v[164:167], v159 offset:2048
	ds_read_b128 v[168:171], v159 offset:3072
	v_add_u32_e32 v159, s33, v153
	ds_read_b128 v[172:175], v159
	ds_read_b128 v[176:179], v159 offset:1024
	ds_read_b128 v[180:183], v159 offset:2048
	ds_read_b128 v[184:187], v159 offset:3072
	s_add_u32 s72, s72, 0x40000
	s_addc_u32 s73, s73, 0
	s_mov_b32 m0, s78
	v_lshl_add_u64 v[226:227], s[72:73], 0, v[130:131]
	ds_read_b128 v[188:191], v157 offset:32768
	ds_read_b128 v[192:195], v157 offset:33792
	ds_read_b128 v[196:199], v157 offset:34816
	ds_read_b128 v[200:203], v157 offset:35840
	ds_read_b128 v[204:207], v157 offset:36864
	ds_read_b128 v[208:211], v157 offset:37888
	ds_read_b128 v[212:215], v157 offset:38912
	ds_read_b128 v[216:219], v157 offset:39936
	global_load_lds_dwordx4 v[226:227], off
	v_lshl_add_u64 v[226:227], s[72:73], 0, v[134:135]
	s_mov_b32 m0, s79
	s_nop 0
	global_load_lds_dwordx4 v[226:227], off
	s_waitcnt vmcnt(8)
	s_waitcnt lgkmcnt(0)
	s_barrier
	s_setprio 1
	s_waitcnt lgkmcnt(0)
	v_mfma_f32_16x16x32_bf16 v[124:127], v[146:149], v[188:191], v[124:127]
	v_mfma_f32_16x16x32_bf16 v[120:123], v[164:167], v[188:191], v[120:123]
	v_mfma_f32_16x16x32_bf16 v[108:111], v[146:149], v[196:199], v[108:111]
	v_mfma_f32_16x16x32_bf16 v[104:107], v[164:167], v[196:199], v[104:107]
	v_mfma_f32_16x16x32_bf16 v[92:95], v[146:149], v[204:207], v[92:95]
	v_mfma_f32_16x16x32_bf16 v[88:91], v[164:167], v[204:207], v[88:91]
	v_mfma_f32_16x16x32_bf16 v[76:79], v[146:149], v[212:215], v[76:79]
	v_mfma_f32_16x16x32_bf16 v[72:75], v[164:167], v[212:215], v[72:75]
	v_mfma_f32_16x16x32_bf16 v[124:127], v[160:163], v[192:195], v[124:127]
	v_mfma_f32_16x16x32_bf16 v[120:123], v[168:171], v[192:195], v[120:123]
	v_mfma_f32_16x16x32_bf16 v[108:111], v[160:163], v[200:203], v[108:111]
	v_mfma_f32_16x16x32_bf16 v[104:107], v[168:171], v[200:203], v[104:107]
	v_mfma_f32_16x16x32_bf16 v[92:95], v[160:163], v[208:211], v[92:95]
	v_mfma_f32_16x16x32_bf16 v[88:91], v[168:171], v[208:211], v[88:91]
	v_mfma_f32_16x16x32_bf16 v[76:79], v[160:163], v[216:219], v[76:79]
	v_mfma_f32_16x16x32_bf16 v[72:75], v[168:171], v[216:219], v[72:75]
	v_mfma_f32_16x16x32_bf16 v[116:119], v[172:175], v[188:191], v[116:119]
	v_mfma_f32_16x16x32_bf16 v[112:115], v[180:183], v[188:191], v[112:115]
	v_mfma_f32_16x16x32_bf16 v[100:103], v[172:175], v[196:199], v[100:103]
	v_mfma_f32_16x16x32_bf16 v[96:99], v[180:183], v[196:199], v[96:99]
	v_mfma_f32_16x16x32_bf16 v[84:87], v[172:175], v[204:207], v[84:87]
	v_mfma_f32_16x16x32_bf16 v[80:83], v[180:183], v[204:207], v[80:83]
	v_mfma_f32_16x16x32_bf16 v[68:71], v[172:175], v[212:215], v[68:71]
	v_mfma_f32_16x16x32_bf16 v[64:67], v[180:183], v[212:215], v[64:67]
	v_mfma_f32_16x16x32_bf16 v[116:119], v[176:179], v[192:195], v[116:119]
	v_mfma_f32_16x16x32_bf16 v[112:115], v[184:187], v[192:195], v[112:115]
	v_mfma_f32_16x16x32_bf16 v[100:103], v[176:179], v[200:203], v[100:103]
	v_mfma_f32_16x16x32_bf16 v[96:99], v[184:187], v[200:203], v[96:99]
	v_mfma_f32_16x16x32_bf16 v[84:87], v[176:179], v[208:211], v[84:87]
	v_mfma_f32_16x16x32_bf16 v[80:83], v[184:187], v[208:211], v[80:83]
	v_mfma_f32_16x16x32_bf16 v[68:71], v[176:179], v[216:219], v[68:71]
	v_mfma_f32_16x16x32_bf16 v[64:67], v[184:187], v[216:219], v[64:67]
	s_setprio 0
	s_barrier
	s_add_i32 s23, s23, s74
	v_lshl_add_u64 v[150:151], v[150:151], 0, s[10:11]
	s_mov_b32 m0, s23
	ds_read_b128 v[188:191], v157 offset:49152
	ds_read_b128 v[192:195], v157 offset:50176
	ds_read_b128 v[196:199], v157 offset:51200
	ds_read_b128 v[200:203], v157 offset:52224
	ds_read_b128 v[204:207], v157 offset:53248
	ds_read_b128 v[208:211], v157 offset:54272
	ds_read_b128 v[212:215], v157 offset:55296
	ds_read_b128 v[216:219], v157 offset:56320
	global_load_lds_dwordx4 v[150:151], off
	s_add_i32 m0, s23, 0x2000
	s_add_u32 s70, s70, 0x40080
	v_lshl_add_u64 v[150:151], v[220:221], 0, s[10:11]
	s_addc_u32 s71, s71, 0
	s_add_i32 s23, s33, s74
	global_load_lds_dwordx4 v[150:151], off
	v_lshl_add_u64 v[150:151], s[70:71], 0, v[132:133]
	s_mov_b32 m0, s23
	s_nop 0
	global_load_lds_dwordx4 v[150:151], off
	v_lshl_add_u64 v[150:151], s[70:71], 0, v[136:137]
	s_add_i32 m0, s23, 0x2000
	s_nop 0
	global_load_lds_dwordx4 v[150:151], off
	v_lshl_add_u64 v[150:151], v[222:223], 0, s[10:11]
	s_mov_b32 m0, s82
	s_nop 0
	global_load_lds_dwordx4 v[150:151], off
	v_lshl_add_u64 v[150:151], v[224:225], 0, s[10:11]
	s_mov_b32 m0, s83
	s_nop 0
	global_load_lds_dwordx4 v[150:151], off
	s_waitcnt vmcnt(8)
	s_waitcnt lgkmcnt(0)
	s_barrier
	s_setprio 1
	s_waitcnt lgkmcnt(0)
	v_mfma_f32_16x16x32_bf16 v[60:63], v[146:149], v[188:191], v[60:63]
	v_mfma_f32_16x16x32_bf16 v[56:59], v[164:167], v[188:191], v[56:59]
	v_mfma_f32_16x16x32_bf16 v[44:47], v[146:149], v[196:199], v[44:47]
	v_mfma_f32_16x16x32_bf16 v[40:43], v[164:167], v[196:199], v[40:43]
	v_mfma_f32_16x16x32_bf16 v[28:31], v[146:149], v[204:207], v[28:31]
	v_mfma_f32_16x16x32_bf16 v[24:27], v[164:167], v[204:207], v[24:27]
	v_mfma_f32_16x16x32_bf16 v[12:15], v[146:149], v[212:215], v[12:15]
	v_mfma_f32_16x16x32_bf16 v[8:11], v[164:167], v[212:215], v[8:11]
	v_mfma_f32_16x16x32_bf16 v[60:63], v[160:163], v[192:195], v[60:63]
	v_mfma_f32_16x16x32_bf16 v[56:59], v[168:171], v[192:195], v[56:59]
	v_mfma_f32_16x16x32_bf16 v[44:47], v[160:163], v[200:203], v[44:47]
	v_mfma_f32_16x16x32_bf16 v[40:43], v[168:171], v[200:203], v[40:43]
	v_mfma_f32_16x16x32_bf16 v[28:31], v[160:163], v[208:211], v[28:31]
	v_mfma_f32_16x16x32_bf16 v[24:27], v[168:171], v[208:211], v[24:27]
	v_mfma_f32_16x16x32_bf16 v[12:15], v[160:163], v[216:219], v[12:15]
	v_mfma_f32_16x16x32_bf16 v[8:11], v[168:171], v[216:219], v[8:11]
	v_mfma_f32_16x16x32_bf16 v[52:55], v[172:175], v[188:191], v[52:55]
	v_mfma_f32_16x16x32_bf16 v[48:51], v[180:183], v[188:191], v[48:51]
	v_mfma_f32_16x16x32_bf16 v[36:39], v[172:175], v[196:199], v[36:39]
	v_mfma_f32_16x16x32_bf16 v[32:35], v[180:183], v[196:199], v[32:35]
	v_mfma_f32_16x16x32_bf16 v[20:23], v[172:175], v[204:207], v[20:23]
	v_mfma_f32_16x16x32_bf16 v[16:19], v[180:183], v[204:207], v[16:19]
	v_mfma_f32_16x16x32_bf16 v[4:7], v[172:175], v[212:215], v[4:7]
	v_mfma_f32_16x16x32_bf16 v[0:3], v[180:183], v[212:215], v[0:3]
	v_mfma_f32_16x16x32_bf16 v[52:55], v[176:179], v[192:195], v[52:55]
	v_mfma_f32_16x16x32_bf16 v[48:51], v[184:187], v[192:195], v[48:51]
	v_mfma_f32_16x16x32_bf16 v[36:39], v[176:179], v[200:203], v[36:39]
	v_mfma_f32_16x16x32_bf16 v[32:35], v[184:187], v[200:203], v[32:35]
	v_mfma_f32_16x16x32_bf16 v[20:23], v[176:179], v[208:211], v[20:23]
	v_mfma_f32_16x16x32_bf16 v[16:19], v[184:187], v[208:211], v[16:19]
	v_mfma_f32_16x16x32_bf16 v[4:7], v[176:179], v[216:219], v[4:7]
	v_mfma_f32_16x16x32_bf16 v[0:3], v[184:187], v[216:219], v[0:3]
	s_setprio 0
	s_barrier
	s_add_i32 s92, s92, 2
	s_add_u32 s64, s64, 0x100
	s_addc_u32 s65, s65, 0
	s_add_u32 s90, s90, 0x100
	s_addc_u32 s91, s91, 0
	s_cmp_gt_u32 s92, 13
	s_cbranch_scc0 .LBB0_295
	s_and_b64 vcc, exec, s[14:15]
	s_cbranch_vccz .LBB0_298
	s_barrier

.LBB0_437:
	ds_read_b128 v[146:149], v139
	ds_read_b128 v[150:153], v139 offset:1024
	ds_read_b128 v[154:157], v139 offset:2048
	ds_read_b128 v[158:161], v139 offset:3072
	ds_read_b128 v[162:165], v141
	ds_read_b128 v[166:169], v141 offset:1024
	ds_read_b128 v[170:173], v141 offset:2048
	ds_read_b128 v[174:177], v141 offset:3072
	s_add_u32 s10, s6, s8
	s_addc_u32 s11, s7, s9
	s_add_u32 s10, s10, 0x2300100
	s_addc_u32 s11, s11, 0
	s_add_u32 s23, s69, s8
	s_addc_u32 s33, s70, s9
	s_cmpk_eq_i32 s8, 0x700
	s_cselect_b32 s13, s3, s11
	s_cselect_b32 s12, s2, s10
	s_cselect_b32 s11, s1, s33
	s_cselect_b32 s10, s0, s23
	s_mov_b32 m0, s72
	v_lshl_add_u64 v[210:211], v[134:135], 0, s[8:9]
	ds_read_b128 v[178:181], v142
	ds_read_b128 v[182:185], v142 offset:1024
	ds_read_b128 v[186:189], v142 offset:2048
	ds_read_b128 v[190:193], v142 offset:3072
	ds_read_b128 v[194:197], v142 offset:4096
	ds_read_b128 v[198:201], v142 offset:5120
	ds_read_b128 v[202:205], v142 offset:6144
	ds_read_b128 v[206:209], v142 offset:7168
	global_load_lds_dwordx4 v[210:211], off
	v_lshl_add_u64 v[210:211], v[136:137], 0, s[8:9]
	s_mov_b32 m0, s73
	s_nop 0
	global_load_lds_dwordx4 v[210:211], off
	s_waitcnt vmcnt(8)
	s_waitcnt lgkmcnt(0)
	s_barrier
	s_setprio 1
	s_waitcnt lgkmcnt(0)
	v_mfma_f32_16x16x32_bf16 v[124:127], v[146:149], v[178:181], v[124:127]
	v_mfma_f32_16x16x32_bf16 v[120:123], v[154:157], v[178:181], v[120:123]
	v_mfma_f32_16x16x32_bf16 v[108:111], v[146:149], v[186:189], v[108:111]
	v_mfma_f32_16x16x32_bf16 v[104:107], v[154:157], v[186:189], v[104:107]
	v_mfma_f32_16x16x32_bf16 v[92:95], v[146:149], v[194:197], v[92:95]
	v_mfma_f32_16x16x32_bf16 v[88:91], v[154:157], v[194:197], v[88:91]
	v_mfma_f32_16x16x32_bf16 v[76:79], v[146:149], v[202:205], v[76:79]
	v_mfma_f32_16x16x32_bf16 v[72:75], v[154:157], v[202:205], v[72:75]
	v_mfma_f32_16x16x32_bf16 v[124:127], v[150:153], v[182:185], v[124:127]
	v_mfma_f32_16x16x32_bf16 v[120:123], v[158:161], v[182:185], v[120:123]
	v_mfma_f32_16x16x32_bf16 v[108:111], v[150:153], v[190:193], v[108:111]
	v_mfma_f32_16x16x32_bf16 v[104:107], v[158:161], v[190:193], v[104:107]
	v_mfma_f32_16x16x32_bf16 v[92:95], v[150:153], v[198:201], v[92:95]
	v_mfma_f32_16x16x32_bf16 v[88:91], v[158:161], v[198:201], v[88:91]
	v_mfma_f32_16x16x32_bf16 v[76:79], v[150:153], v[206:209], v[76:79]
	v_mfma_f32_16x16x32_bf16 v[72:75], v[158:161], v[206:209], v[72:75]
	v_mfma_f32_16x16x32_bf16 v[116:119], v[162:165], v[178:181], v[116:119]
	v_mfma_f32_16x16x32_bf16 v[112:115], v[170:173], v[178:181], v[112:115]
	v_mfma_f32_16x16x32_bf16 v[100:103], v[162:165], v[186:189], v[100:103]
	v_mfma_f32_16x16x32_bf16 v[96:99], v[170:173], v[186:189], v[96:99]
	v_mfma_f32_16x16x32_bf16 v[84:87], v[162:165], v[194:197], v[84:87]
	v_mfma_f32_16x16x32_bf16 v[80:83], v[170:173], v[194:197], v[80:83]
	v_mfma_f32_16x16x32_bf16 v[68:71], v[162:165], v[202:205], v[68:71]
	v_mfma_f32_16x16x32_bf16 v[64:67], v[170:173], v[202:205], v[64:67]
	v_mfma_f32_16x16x32_bf16 v[116:119], v[166:169], v[182:185], v[116:119]
	v_mfma_f32_16x16x32_bf16 v[112:115], v[174:177], v[182:185], v[112:115]
	v_mfma_f32_16x16x32_bf16 v[100:103], v[166:169], v[190:193], v[100:103]
	v_mfma_f32_16x16x32_bf16 v[96:99], v[174:177], v[190:193], v[96:99]
	v_mfma_f32_16x16x32_bf16 v[84:87], v[166:169], v[198:201], v[84:87]
	v_mfma_f32_16x16x32_bf16 v[80:83], v[174:177], v[198:201], v[80:83]
	v_mfma_f32_16x16x32_bf16 v[68:71], v[166:169], v[206:209], v[68:71]
	v_mfma_f32_16x16x32_bf16 v[64:67], v[174:177], v[206:209], v[64:67]
	s_setprio 0
	s_barrier
	s_mov_b32 m0, s74
	v_lshl_add_u64 v[210:211], s[10:11], 0, v[132:133]
	s_add_u32 s82, s10, 0x40000
	ds_read_b128 v[178:181], v142 offset:16384
	ds_read_b128 v[182:185], v142 offset:17408
	ds_read_b128 v[186:189], v142 offset:18432
	ds_read_b128 v[190:193], v142 offset:19456
	ds_read_b128 v[194:197], v142 offset:20480
	ds_read_b128 v[198:201], v142 offset:21504
	ds_read_b128 v[202:205], v142 offset:22528
	ds_read_b128 v[206:209], v142 offset:23552
	global_load_lds_dwordx4 v[210:211], off
	v_lshl_add_u64 v[212:213], s[10:11], 0, v[130:131]
	s_mov_b32 m0, s75
	s_addc_u32 s83, s11, 0
	global_load_lds_dwordx4 v[212:213], off
	v_lshl_add_u64 v[214:215], s[82:83], 0, v[132:133]
	s_mov_b32 m0, s76
	v_lshl_add_u64 v[216:217], s[12:13], 0, v[130:131]
	global_load_lds_dwordx4 v[214:215], off
	v_lshl_add_u64 v[214:215], s[82:83], 0, v[130:131]
	s_mov_b32 m0, s77
	s_nop 0
	global_load_lds_dwordx4 v[214:215], off
	v_lshl_add_u64 v[214:215], s[12:13], 0, v[132:133]
	s_mov_b32 m0, s17
	s_nop 0
	global_load_lds_dwordx4 v[214:215], off
	s_mov_b32 m0, s20
	s_nop 0
	global_load_lds_dwordx4 v[216:217], off
	s_waitcnt vmcnt(8)
	s_waitcnt lgkmcnt(0)
	s_barrier
	s_setprio 1
	s_waitcnt lgkmcnt(0)
	v_mfma_f32_16x16x32_bf16 v[60:63], v[146:149], v[178:181], v[60:63]
	v_mfma_f32_16x16x32_bf16 v[56:59], v[154:157], v[178:181], v[56:59]
	v_mfma_f32_16x16x32_bf16 v[44:47], v[146:149], v[186:189], v[44:47]
	v_mfma_f32_16x16x32_bf16 v[40:43], v[154:157], v[186:189], v[40:43]
	v_mfma_f32_16x16x32_bf16 v[28:31], v[146:149], v[194:197], v[28:31]
	v_mfma_f32_16x16x32_bf16 v[24:27], v[154:157], v[194:197], v[24:27]
	v_mfma_f32_16x16x32_bf16 v[12:15], v[146:149], v[202:205], v[12:15]
	v_mfma_f32_16x16x32_bf16 v[8:11], v[154:157], v[202:205], v[8:11]
	v_mfma_f32_16x16x32_bf16 v[60:63], v[150:153], v[182:185], v[60:63]
	v_mfma_f32_16x16x32_bf16 v[56:59], v[158:161], v[182:185], v[56:59]
	v_mfma_f32_16x16x32_bf16 v[44:47], v[150:153], v[190:193], v[44:47]
	v_mfma_f32_16x16x32_bf16 v[40:43], v[158:161], v[190:193], v[40:43]
	v_mfma_f32_16x16x32_bf16 v[28:31], v[150:153], v[198:201], v[28:31]
	v_mfma_f32_16x16x32_bf16 v[24:27], v[158:161], v[198:201], v[24:27]
	v_mfma_f32_16x16x32_bf16 v[12:15], v[150:153], v[206:209], v[12:15]
	v_mfma_f32_16x16x32_bf16 v[8:11], v[158:161], v[206:209], v[8:11]
	v_mfma_f32_16x16x32_bf16 v[52:55], v[162:165], v[178:181], v[52:55]
	v_mfma_f32_16x16x32_bf16 v[48:51], v[170:173], v[178:181], v[48:51]
	v_mfma_f32_16x16x32_bf16 v[36:39], v[162:165], v[186:189], v[36:39]
	v_mfma_f32_16x16x32_bf16 v[32:35], v[170:173], v[186:189], v[32:35]
	v_mfma_f32_16x16x32_bf16 v[20:23], v[162:165], v[194:197], v[20:23]
	v_mfma_f32_16x16x32_bf16 v[16:19], v[170:173], v[194:197], v[16:19]
	v_mfma_f32_16x16x32_bf16 v[4:7], v[162:165], v[202:205], v[4:7]
	v_mfma_f32_16x16x32_bf16 v[0:3], v[170:173], v[202:205], v[0:3]
	v_mfma_f32_16x16x32_bf16 v[52:55], v[166:169], v[182:185], v[52:55]
	v_mfma_f32_16x16x32_bf16 v[48:51], v[174:177], v[182:185], v[48:51]
	v_mfma_f32_16x16x32_bf16 v[36:39], v[166:169], v[190:193], v[36:39]
	v_mfma_f32_16x16x32_bf16 v[32:35], v[174:177], v[190:193], v[32:35]
	v_mfma_f32_16x16x32_bf16 v[20:23], v[166:169], v[198:201], v[20:23]
	v_mfma_f32_16x16x32_bf16 v[16:19], v[174:177], v[198:201], v[16:19]
	v_mfma_f32_16x16x32_bf16 v[4:7], v[166:169], v[206:209], v[4:7]
	v_mfma_f32_16x16x32_bf16 v[0:3], v[174:177], v[206:209], v[0:3]
	s_setprio 0
	s_barrier
	ds_read_b128 v[146:149], v143
	ds_read_b128 v[150:153], v143 offset:1024
	ds_read_b128 v[154:157], v143 offset:2048
	ds_read_b128 v[158:161], v143 offset:3072
	ds_read_b128 v[162:165], v144
	ds_read_b128 v[166:169], v144 offset:1024
	ds_read_b128 v[170:173], v144 offset:2048
	ds_read_b128 v[174:177], v144 offset:3072
	s_add_u32 s12, s12, 0x40000
	s_addc_u32 s13, s13, 0
	s_mov_b32 m0, s21
	v_lshl_add_u64 v[218:219], s[12:13], 0, v[132:133]
	ds_read_b128 v[178:181], v142 offset:32768
	ds_read_b128 v[182:185], v142 offset:33792
	ds_read_b128 v[186:189], v142 offset:34816
	ds_read_b128 v[190:193], v142 offset:35840
	ds_read_b128 v[194:197], v142 offset:36864
	ds_read_b128 v[198:201], v142 offset:37888
	ds_read_b128 v[202:205], v142 offset:38912
	ds_read_b128 v[206:209], v142 offset:39936
	global_load_lds_dwordx4 v[218:219], off
	v_lshl_add_u64 v[218:219], s[12:13], 0, v[130:131]
	s_mov_b32 m0, s58
	s_nop 0
	global_load_lds_dwordx4 v[218:219], off
	s_waitcnt vmcnt(8)
	s_waitcnt lgkmcnt(0)
	s_barrier
	s_setprio 1
	s_waitcnt lgkmcnt(0)
	v_mfma_f32_16x16x32_bf16 v[124:127], v[146:149], v[178:181], v[124:127]
	v_mfma_f32_16x16x32_bf16 v[120:123], v[154:157], v[178:181], v[120:123]
	v_mfma_f32_16x16x32_bf16 v[108:111], v[146:149], v[186:189], v[108:111]
	v_mfma_f32_16x16x32_bf16 v[104:107], v[154:157], v[186:189], v[104:107]
	v_mfma_f32_16x16x32_bf16 v[92:95], v[146:149], v[194:197], v[92:95]
	v_mfma_f32_16x16x32_bf16 v[88:91], v[154:157], v[194:197], v[88:91]
	v_mfma_f32_16x16x32_bf16 v[76:79], v[146:149], v[202:205], v[76:79]
	v_mfma_f32_16x16x32_bf16 v[72:75], v[154:157], v[202:205], v[72:75]
	v_mfma_f32_16x16x32_bf16 v[124:127], v[150:153], v[182:185], v[124:127]
	v_mfma_f32_16x16x32_bf16 v[120:123], v[158:161], v[182:185], v[120:123]
	v_mfma_f32_16x16x32_bf16 v[108:111], v[150:153], v[190:193], v[108:111]
	v_mfma_f32_16x16x32_bf16 v[104:107], v[158:161], v[190:193], v[104:107]
	v_mfma_f32_16x16x32_bf16 v[92:95], v[150:153], v[198:201], v[92:95]
	v_mfma_f32_16x16x32_bf16 v[88:91], v[158:161], v[198:201], v[88:91]
	v_mfma_f32_16x16x32_bf16 v[76:79], v[150:153], v[206:209], v[76:79]
	v_mfma_f32_16x16x32_bf16 v[72:75], v[158:161], v[206:209], v[72:75]
	v_mfma_f32_16x16x32_bf16 v[116:119], v[162:165], v[178:181], v[116:119]
	v_mfma_f32_16x16x32_bf16 v[112:115], v[170:173], v[178:181], v[112:115]
	v_mfma_f32_16x16x32_bf16 v[100:103], v[162:165], v[186:189], v[100:103]
	v_mfma_f32_16x16x32_bf16 v[96:99], v[170:173], v[186:189], v[96:99]
	v_mfma_f32_16x16x32_bf16 v[84:87], v[162:165], v[194:197], v[84:87]
	v_mfma_f32_16x16x32_bf16 v[80:83], v[170:173], v[194:197], v[80:83]
	v_mfma_f32_16x16x32_bf16 v[68:71], v[162:165], v[202:205], v[68:71]
	v_mfma_f32_16x16x32_bf16 v[64:67], v[170:173], v[202:205], v[64:67]
	v_mfma_f32_16x16x32_bf16 v[116:119], v[166:169], v[182:185], v[116:119]
	v_mfma_f32_16x16x32_bf16 v[112:115], v[174:177], v[182:185], v[112:115]
	v_mfma_f32_16x16x32_bf16 v[100:103], v[166:169], v[190:193], v[100:103]
	v_mfma_f32_16x16x32_bf16 v[96:99], v[174:177], v[190:193], v[96:99]
	v_mfma_f32_16x16x32_bf16 v[84:87], v[166:169], v[198:201], v[84:87]
	v_mfma_f32_16x16x32_bf16 v[80:83], v[174:177], v[198:201], v[80:83]
	v_mfma_f32_16x16x32_bf16 v[68:71], v[166:169], v[206:209], v[68:71]
	v_mfma_f32_16x16x32_bf16 v[64:67], v[174:177], v[206:209], v[64:67]
	s_setprio 0
	s_barrier
	s_mov_b32 m0, s78
	v_lshl_add_u64 v[210:211], v[210:211], 0, s[4:5]
	s_add_u32 s10, s10, 0x40080
	ds_read_b128 v[178:181], v142 offset:49152
	ds_read_b128 v[182:185], v142 offset:50176
	ds_read_b128 v[186:189], v142 offset:51200
	ds_read_b128 v[190:193], v142 offset:52224
	ds_read_b128 v[194:197], v142 offset:53248
	ds_read_b128 v[198:201], v142 offset:54272
	ds_read_b128 v[202:205], v142 offset:55296
	ds_read_b128 v[206:209], v142 offset:56320
	global_load_lds_dwordx4 v[210:211], off
	v_lshl_add_u64 v[210:211], v[212:213], 0, s[4:5]
	s_mov_b32 m0, s79
	s_addc_u32 s11, s11, 0
	global_load_lds_dwordx4 v[210:211], off
	v_lshl_add_u64 v[210:211], s[10:11], 0, v[132:133]
	s_mov_b32 m0, s80
	s_nop 0
	global_load_lds_dwordx4 v[210:211], off
	v_lshl_add_u64 v[210:211], s[10:11], 0, v[130:131]
	s_mov_b32 m0, s81
	s_nop 0
	global_load_lds_dwordx4 v[210:211], off
	v_lshl_add_u64 v[210:211], v[214:215], 0, s[4:5]
	s_mov_b32 m0, s65
	s_nop 0
	global_load_lds_dwordx4 v[210:211], off
	v_lshl_add_u64 v[210:211], v[216:217], 0, s[4:5]
	s_mov_b32 m0, s68
	s_nop 0
	global_load_lds_dwordx4 v[210:211], off
	s_waitcnt vmcnt(8)
	s_waitcnt lgkmcnt(0)
	s_barrier
	s_setprio 1
	s_waitcnt lgkmcnt(0)
	v_mfma_f32_16x16x32_bf16 v[60:63], v[146:149], v[178:181], v[60:63]
	v_mfma_f32_16x16x32_bf16 v[56:59], v[154:157], v[178:181], v[56:59]
	v_mfma_f32_16x16x32_bf16 v[44:47], v[146:149], v[186:189], v[44:47]
	v_mfma_f32_16x16x32_bf16 v[40:43], v[154:157], v[186:189], v[40:43]
	v_mfma_f32_16x16x32_bf16 v[28:31], v[146:149], v[194:197], v[28:31]
	v_mfma_f32_16x16x32_bf16 v[24:27], v[154:157], v[194:197], v[24:27]
	v_mfma_f32_16x16x32_bf16 v[12:15], v[146:149], v[202:205], v[12:15]
	v_mfma_f32_16x16x32_bf16 v[8:11], v[154:157], v[202:205], v[8:11]
	v_mfma_f32_16x16x32_bf16 v[60:63], v[150:153], v[182:185], v[60:63]
	v_mfma_f32_16x16x32_bf16 v[56:59], v[158:161], v[182:185], v[56:59]
	v_mfma_f32_16x16x32_bf16 v[44:47], v[150:153], v[190:193], v[44:47]
	v_mfma_f32_16x16x32_bf16 v[40:43], v[158:161], v[190:193], v[40:43]
	v_mfma_f32_16x16x32_bf16 v[28:31], v[150:153], v[198:201], v[28:31]
	v_mfma_f32_16x16x32_bf16 v[24:27], v[158:161], v[198:201], v[24:27]
	v_mfma_f32_16x16x32_bf16 v[12:15], v[150:153], v[206:209], v[12:15]
	v_mfma_f32_16x16x32_bf16 v[8:11], v[158:161], v[206:209], v[8:11]
	v_mfma_f32_16x16x32_bf16 v[52:55], v[162:165], v[178:181], v[52:55]
	v_mfma_f32_16x16x32_bf16 v[48:51], v[170:173], v[178:181], v[48:51]
	v_mfma_f32_16x16x32_bf16 v[36:39], v[162:165], v[186:189], v[36:39]
	v_mfma_f32_16x16x32_bf16 v[32:35], v[170:173], v[186:189], v[32:35]
	v_mfma_f32_16x16x32_bf16 v[20:23], v[162:165], v[194:197], v[20:23]
	v_mfma_f32_16x16x32_bf16 v[16:19], v[170:173], v[194:197], v[16:19]
	v_mfma_f32_16x16x32_bf16 v[4:7], v[162:165], v[202:205], v[4:7]
	v_mfma_f32_16x16x32_bf16 v[0:3], v[170:173], v[202:205], v[0:3]
	v_mfma_f32_16x16x32_bf16 v[52:55], v[166:169], v[182:185], v[52:55]
	v_mfma_f32_16x16x32_bf16 v[48:51], v[174:177], v[182:185], v[48:51]
	v_mfma_f32_16x16x32_bf16 v[36:39], v[166:169], v[190:193], v[36:39]
	v_mfma_f32_16x16x32_bf16 v[32:35], v[174:177], v[190:193], v[32:35]
	v_mfma_f32_16x16x32_bf16 v[20:23], v[166:169], v[198:201], v[20:23]
	v_mfma_f32_16x16x32_bf16 v[16:19], v[174:177], v[198:201], v[16:19]
	v_mfma_f32_16x16x32_bf16 v[4:7], v[166:169], v[206:209], v[4:7]
	v_mfma_f32_16x16x32_bf16 v[0:3], v[174:177], v[206:209], v[0:3]
	s_setprio 0
	s_barrier
	s_add_i32 s71, s71, 2
	s_add_u32 s8, s8, 0x100
	s_addc_u32 s9, s9, 0
	s_cmp_gt_u32 s71, 13
	s_cbranch_scc0 .LBB0_437
	s_add_u32 s4, s28, 0x2f41000
	s_addc_u32 s5, s29, 0
	s_lshl_b32 s0, s16, 8
	s_add_i32 s64, s64, s0
	v_or_b32_e32 v130, s64, v140
	v_mov_b32_e32 v131, 0
	v_lshl_add_u64 v[132:133], v[130:131], 2, s[4:5]
	global_load_dword v149, v[132:133], off
	v_lshl_or_b32 v134, v138, 2, s59
	v_mov_b32_e32 v148, 0x358637bd
	s_lshl_b32 s13, s15, 8
	s_mov_b32 s6, 0x800000
	s_movk_i32 s0, 0x36c
	v_or_b32_e32 v146, s13, v134
	s_and_b32 s9, s13, 0x300
	v_mov_b32_e32 v150, s13
	s_lshl_b32 s13, s64, 2
	v_mov_b32_e32 v142, 0x80
	s_movk_i32 s10, 0xec
	v_lshlrev_b32_e32 v138, 1, v134
	v_bitop3_b32 v134, v134, s0, v150 bitop3:0xc8
	s_and_b32 s0, s13, 0xfffffc00
	v_bitop3_b32 v154, v146, s10, v142 bitop3:0xc8
	s_or_b32 s10, s0, s9
	s_mov_b32 s1, 0x4880000
	s_cmp_gt_u32 s15, 3
	v_mov_b32_e32 v136, 0xcf
	s_mov_b32 s2, 0x2b00000
	s_cselect_b32 s0, s1, 0x4080000
	s_movk_i32 s3, 0x37c
	s_movk_i32 s8, 0x3ec
	v_bitop3_b32 v152, s64, v136, v140 bitop3:0xc8
	s_cselect_b32 s1, s2, 0x2700000
	s_add_u32 s2, s26, s0
	v_bitop3_b32 v136, v146, s3, 16 bitop3:0xc8
	v_bitop3_b32 v153, v146, s8, v142 bitop3:0xc8
	v_or_b32_e32 v152, s10, v152
	s_addc_u32 s3, s27, 0
	s_movk_i32 s7, 0x7c
	s_movk_i32 s11, 0x3fc
	v_mov_b32_e32 v144, 0x90
	s_movk_i32 s12, 0xfc
	v_lshlrev_b64 v[150:151], 12, v[130:131]
	v_lshlrev_b32_e32 v142, 2, v153
	v_ashrrev_i32_e32 v153, 31, v152
	s_add_u32 s0, s28, s1
	v_mov_b32_e32 v147, v131
	v_bitop3_b32 v140, v146, s7, 16 bitop3:0xc8
	v_bitop3_b32 v155, v146, s11, v144 bitop3:0xc8
	v_bitop3_b32 v167, v146, s12, v144 bitop3:0xc8
	v_lshlrev_b32_e32 v146, 2, v134
	v_lshlrev_b64 v[152:153], 9, v[152:153]
	v_lshl_add_u64 v[150:151], s[2:3], 0, v[150:151]
	s_addc_u32 s1, s29, 0
	v_mov_b32_e32 v139, v131
	v_lshlrev_b32_e32 v144, 2, v136
	v_lshlrev_b32_e32 v134, 1, v140
	v_lshlrev_b32_e32 v136, 1, v154
	v_lshlrev_b32_e32 v140, 2, v155
	v_lshl_add_u64 v[154:155], v[150:151], 0, v[146:147]
	v_lshl_add_u64 v[152:153], s[0:1], 0, v[152:153]
	v_mov_b32_e32 v145, v131
	v_mov_b32_e32 v135, v131
	v_mov_b32_e32 v143, v131
	v_mov_b32_e32 v137, v131
	v_lshl_add_u64 v[156:157], v[150:151], 0, v[144:145]
	v_lshl_add_u64 v[162:163], v[152:153], 0, v[134:135]
	v_mov_b32_e32 v141, v131
	v_lshl_add_u64 v[158:159], v[150:151], 0, v[142:143]
	v_lshl_add_u64 v[164:165], v[152:153], 0, v[136:137]
	v_lshl_add_u64 v[150:151], v[150:151], 0, v[140:141]
	s_movk_i32 s7, 0xdf
	s_movk_i32 s8, 0xef
	s_cmpk_lt_u32 s14, 0x100
	s_waitcnt vmcnt(0)
	v_fmamk_f32 v149, v149, 0x3a800000, v148
	v_mul_f32_e32 v160, 0x4b800000, v149
	v_cmp_gt_f32_e32 vcc, s6, v149
	s_nop 1
	v_cndmask_b32_e32 v149, v149, v160, vcc
	v_rsq_f32_e32 v149, v149
	v_lshl_add_u64 v[160:161], v[152:153], 0, v[138:139]
	v_mul_f32_e32 v166, 0x45800000, v149
	v_cndmask_b32_e32 v166, v149, v166, vcc
	v_pk_mul_f32 v[126:127], v[126:127], v[166:167] op_sel_hi:[1,0]
	v_pk_mul_f32 v[124:125], v[124:125], v[166:167] op_sel_hi:[1,0]
	v_pk_mul_f32 v[120:121], v[120:121], v[166:167] op_sel_hi:[1,0]
	global_store_dwordx4 v[154:155], v[124:127], off
	v_pk_mul_f32 v[122:123], v[122:123], v[166:167] op_sel_hi:[1,0]
	v_pk_mul_f32 v[116:117], v[116:117], v[166:167] op_sel_hi:[1,0]
	v_cvt_pk_bf16_f32 v124, v124, v125
	v_cvt_pk_bf16_f32 v125, v126, v127
	global_store_dwordx2 v[160:161], v[124:125], off
	global_store_dwordx4 v[156:157], v[120:123], off
	v_pk_mul_f32 v[118:119], v[118:119], v[166:167] op_sel_hi:[1,0]
	v_pk_mul_f32 v[112:113], v[112:113], v[166:167] op_sel_hi:[1,0]
	v_cvt_pk_bf16_f32 v120, v120, v121
	v_cvt_pk_bf16_f32 v121, v122, v123
	global_store_dwordx2 v[162:163], v[120:121], off
	global_store_dwordx4 v[158:159], v[116:119], off
	v_pk_mul_f32 v[114:115], v[114:115], v[166:167] op_sel_hi:[1,0]
	v_bitop3_b32 v120, v130, s7, 16 bitop3:0xc8
	v_cvt_pk_bf16_f32 v116, v116, v117
	v_cvt_pk_bf16_f32 v117, v118, v119
	global_store_dwordx2 v[164:165], v[116:117], off
	global_store_dwordx4 v[150:151], v[112:115], off
	v_cvt_pk_bf16_f32 v116, v112, v113
	v_cvt_pk_bf16_f32 v117, v114, v115
	v_or_b32_e32 v120, s10, v120
	v_ashrrev_i32_e32 v121, 31, v120
	v_lshlrev_b32_e32 v112, 1, v167
	v_mov_b32_e32 v113, v131
	v_lshl_add_u64 v[114:115], v[152:153], 0, v[112:113]
	global_store_dwordx2 v[114:115], v[116:117], off
	v_or_b32_e32 v114, 16, v130
	v_mov_b32_e32 v115, v131
	v_lshl_add_u64 v[116:117], v[114:115], 2, s[4:5]
	global_load_dword v149, v[116:117], off
	v_lshlrev_b64 v[114:115], 12, v[114:115]
	v_lshlrev_b64 v[120:121], 9, v[120:121]
	v_lshl_add_u64 v[114:115], s[2:3], 0, v[114:115]
	v_lshl_add_u64 v[122:123], v[114:115], 0, v[146:147]
	v_lshl_add_u64 v[120:121], s[0:1], 0, v[120:121]
	v_lshl_add_u64 v[150:151], v[120:121], 0, v[138:139]
	v_lshl_add_u64 v[124:125], v[114:115], 0, v[144:145]
	v_mov_b32_e32 v117, v131
	v_or_b32_e32 v116, 32, v130
	v_lshl_add_u64 v[126:127], v[114:115], 0, v[142:143]
	v_lshl_add_u64 v[154:155], v[120:121], 0, v[136:137]
	v_lshl_add_u64 v[118:119], v[116:117], 2, s[4:5]
	v_lshl_add_u64 v[114:115], v[114:115], 0, v[140:141]
	s_waitcnt vmcnt(0)
	v_fmamk_f32 v149, v149, 0x3a800000, v148
	v_mul_f32_e32 v152, 0x4b800000, v149
	v_cmp_gt_f32_e32 vcc, s6, v149
	s_nop 1
	v_cndmask_b32_e32 v149, v149, v152, vcc
	v_rsq_f32_e32 v149, v149
	v_lshl_add_u64 v[152:153], v[120:121], 0, v[134:135]
	v_lshl_add_u64 v[120:121], v[120:121], 0, v[112:113]
	v_mul_f32_e32 v156, 0x45800000, v149
	v_cndmask_b32_e32 v156, v149, v156, vcc
	v_pk_mul_f32 v[110:111], v[110:111], v[156:157] op_sel_hi:[1,0]
	v_pk_mul_f32 v[108:109], v[108:109], v[156:157] op_sel_hi:[1,0]
	v_pk_mul_f32 v[104:105], v[104:105], v[156:157] op_sel_hi:[1,0]
	global_store_dwordx4 v[122:123], v[108:111], off
	v_pk_mul_f32 v[106:107], v[106:107], v[156:157] op_sel_hi:[1,0]
	v_pk_mul_f32 v[100:101], v[100:101], v[156:157] op_sel_hi:[1,0]
	v_cvt_pk_bf16_f32 v108, v108, v109
	v_cvt_pk_bf16_f32 v109, v110, v111
	global_store_dwordx2 v[150:151], v[108:109], off
	global_store_dwordx4 v[124:125], v[104:107], off
	v_pk_mul_f32 v[102:103], v[102:103], v[156:157] op_sel_hi:[1,0]
	v_pk_mul_f32 v[96:97], v[96:97], v[156:157] op_sel_hi:[1,0]
	v_cvt_pk_bf16_f32 v104, v104, v105
	v_cvt_pk_bf16_f32 v105, v106, v107
	global_store_dwordx2 v[152:153], v[104:105], off
	global_store_dwordx4 v[126:127], v[100:103], off
	v_pk_mul_f32 v[98:99], v[98:99], v[156:157] op_sel_hi:[1,0]
	s_nop 0
	v_cvt_pk_bf16_f32 v100, v100, v101
	v_cvt_pk_bf16_f32 v101, v102, v103
	global_store_dwordx2 v[154:155], v[100:101], off
	global_store_dwordx4 v[114:115], v[96:99], off
	v_bitop3_b32 v102, v130, s8, 32 bitop3:0xc8
	v_or_b32_e32 v102, s10, v102
	v_cvt_pk_bf16_f32 v96, v96, v97
	v_cvt_pk_bf16_f32 v97, v98, v99
	global_store_dwordx2 v[120:121], v[96:97], off
	global_load_dword v114, v[118:119], off
	v_lshlrev_b64 v[98:99], 12, v[116:117]
	v_ashrrev_i32_e32 v103, 31, v102
	v_lshlrev_b64 v[102:103], 9, v[102:103]
	v_lshl_add_u64 v[98:99], s[2:3], 0, v[98:99]
	v_lshl_add_u64 v[104:105], v[98:99], 0, v[146:147]
	v_lshl_add_u64 v[102:103], s[0:1], 0, v[102:103]
	v_lshl_add_u64 v[110:111], v[102:103], 0, v[138:139]
	v_lshl_add_u64 v[106:107], v[98:99], 0, v[144:145]
	v_mov_b32_e32 v97, v131
	v_or_b32_e32 v96, 48, v130
	v_lshl_add_u64 v[108:109], v[98:99], 0, v[142:143]
	v_lshl_add_u64 v[116:117], v[102:103], 0, v[136:137]
	v_lshl_add_u64 v[100:101], v[96:97], 2, s[4:5]
	v_lshl_add_u64 v[98:99], v[98:99], 0, v[140:141]
	s_movk_i32 s4, 0xff
	s_movk_i32 s5, 0xcf
	s_waitcnt vmcnt(0)
	v_fmamk_f32 v114, v114, 0x3a800000, v148
	v_mul_f32_e32 v115, 0x4b800000, v114
	v_cmp_gt_f32_e32 vcc, s6, v114
	s_nop 1
	v_cndmask_b32_e32 v114, v114, v115, vcc
	v_rsq_f32_e32 v118, v114
	v_lshl_add_u64 v[114:115], v[102:103], 0, v[134:135]
	v_lshl_add_u64 v[102:103], v[102:103], 0, v[112:113]
	v_mul_f32_e32 v119, 0x45800000, v118
	v_cndmask_b32_e32 v118, v118, v119, vcc
	v_pk_mul_f32 v[94:95], v[94:95], v[118:119] op_sel_hi:[1,0]
	v_pk_mul_f32 v[92:93], v[92:93], v[118:119] op_sel_hi:[1,0]
	v_pk_mul_f32 v[88:89], v[88:89], v[118:119] op_sel_hi:[1,0]
	global_store_dwordx4 v[104:105], v[92:95], off
	v_pk_mul_f32 v[90:91], v[90:91], v[118:119] op_sel_hi:[1,0]
	v_pk_mul_f32 v[84:85], v[84:85], v[118:119] op_sel_hi:[1,0]
	v_cvt_pk_bf16_f32 v92, v92, v93
	v_cvt_pk_bf16_f32 v93, v94, v95
	global_store_dwordx2 v[110:111], v[92:93], off
	global_store_dwordx4 v[106:107], v[88:91], off
	v_pk_mul_f32 v[86:87], v[86:87], v[118:119] op_sel_hi:[1,0]
	v_pk_mul_f32 v[80:81], v[80:81], v[118:119] op_sel_hi:[1,0]
	v_cvt_pk_bf16_f32 v88, v88, v89
	v_cvt_pk_bf16_f32 v89, v90, v91
	global_store_dwordx2 v[114:115], v[88:89], off
	global_store_dwordx4 v[108:109], v[84:87], off
	v_pk_mul_f32 v[82:83], v[82:83], v[118:119] op_sel_hi:[1,0]
	s_nop 0
	v_cvt_pk_bf16_f32 v84, v84, v85
	v_cvt_pk_bf16_f32 v85, v86, v87
	global_store_dwordx2 v[116:117], v[84:85], off
	global_store_dwordx4 v[98:99], v[80:83], off
	s_nop 1
	v_cvt_pk_bf16_f32 v80, v80, v81
	v_cvt_pk_bf16_f32 v81, v82, v83
	global_store_dwordx2 v[102:103], v[80:81], off
	global_load_dword v92, v[100:101], off
	v_lshlrev_b64 v[80:81], 12, v[96:97]
	v_bitop3_b32 v82, v130, s4, 48 bitop3:0xc8
	v_or_b32_e32 v82, s10, v82
	v_ashrrev_i32_e32 v83, 31, v82
	v_lshlrev_b64 v[82:83], 9, v[82:83]
	v_lshl_add_u64 v[80:81], s[2:3], 0, v[80:81]
	v_lshl_add_u64 v[84:85], v[80:81], 0, v[146:147]
	v_lshl_add_u64 v[82:83], s[0:1], 0, v[82:83]
	v_lshl_add_u64 v[90:91], v[82:83], 0, v[138:139]
	v_lshl_add_u64 v[86:87], v[80:81], 0, v[144:145]
	v_lshl_add_u64 v[88:89], v[80:81], 0, v[142:143]
	v_lshl_add_u64 v[94:95], v[82:83], 0, v[136:137]
	v_lshl_add_u64 v[80:81], v[80:81], 0, v[140:141]
	s_waitcnt vmcnt(0)
	v_fmamk_f32 v92, v92, 0x3a800000, v148
	v_mul_f32_e32 v93, 0x4b800000, v92
	v_cmp_gt_f32_e32 vcc, s6, v92
	s_nop 1
	v_cndmask_b32_e32 v92, v92, v93, vcc
	v_rsq_f32_e32 v96, v92
	v_lshl_add_u64 v[92:93], v[82:83], 0, v[134:135]
	v_lshl_add_u64 v[82:83], v[82:83], 0, v[112:113]
	v_mul_f32_e32 v97, 0x45800000, v96
	v_cndmask_b32_e32 v96, v96, v97, vcc
	v_pk_mul_f32 v[78:79], v[78:79], v[96:97] op_sel_hi:[1,0]
	v_pk_mul_f32 v[76:77], v[76:77], v[96:97] op_sel_hi:[1,0]
	v_pk_mul_f32 v[72:73], v[72:73], v[96:97] op_sel_hi:[1,0]
	global_store_dwordx4 v[84:85], v[76:79], off
	v_pk_mul_f32 v[74:75], v[74:75], v[96:97] op_sel_hi:[1,0]
	v_pk_mul_f32 v[68:69], v[68:69], v[96:97] op_sel_hi:[1,0]
	v_cvt_pk_bf16_f32 v76, v76, v77
	v_cvt_pk_bf16_f32 v77, v78, v79
	global_store_dwordx2 v[90:91], v[76:77], off
	global_store_dwordx4 v[86:87], v[72:75], off
	v_pk_mul_f32 v[70:71], v[70:71], v[96:97] op_sel_hi:[1,0]
	v_pk_mul_f32 v[64:65], v[64:65], v[96:97] op_sel_hi:[1,0]
	v_cvt_pk_bf16_f32 v72, v72, v73
	v_cvt_pk_bf16_f32 v73, v74, v75
	global_store_dwordx2 v[92:93], v[72:73], off
	global_store_dwordx4 v[88:89], v[68:71], off
	v_pk_mul_f32 v[66:67], v[66:67], v[96:97] op_sel_hi:[1,0]
	s_nop 0
	v_cvt_pk_bf16_f32 v68, v68, v69
	v_cvt_pk_bf16_f32 v69, v70, v71
	global_store_dwordx2 v[94:95], v[68:69], off
	global_store_dwordx4 v[80:81], v[64:67], off
	s_nop 1
	v_cvt_pk_bf16_f32 v64, v64, v65
	v_cvt_pk_bf16_f32 v65, v66, v67
	global_store_dwordx2 v[82:83], v[64:65], off
	global_load_dword v76, v[132:133], off offset:512
	v_add_u32_e32 v64, 0x80, v130
	v_mov_b32_e32 v65, v131
	v_lshlrev_b32_e32 v68, 2, v64
	v_lshlrev_b64 v[66:67], 12, v[64:65]
	v_and_b32_e32 v65, 0xfffffc00, v68
	v_or_b32_e32 v81, s9, v65
	v_and_or_b32 v64, v64, s5, v81
	v_ashrrev_i32_e32 v65, 31, v64
	v_lshlrev_b64 v[64:65], 9, v[64:65]
	v_lshl_add_u64 v[66:67], s[2:3], 0, v[66:67]
	v_lshl_add_u64 v[68:69], v[66:67], 0, v[146:147]
	v_lshl_add_u64 v[64:65], s[0:1], 0, v[64:65]
	v_lshl_add_u64 v[74:75], v[64:65], 0, v[138:139]
	v_lshl_add_u64 v[70:71], v[66:67], 0, v[144:145]
	v_lshl_add_u64 v[72:73], v[66:67], 0, v[142:143]
	v_lshl_add_u64 v[78:79], v[64:65], 0, v[136:137]
	v_lshl_add_u64 v[66:67], v[66:67], 0, v[140:141]
	s_waitcnt vmcnt(0)
	v_fmamk_f32 v76, v76, 0x3a800000, v148
	v_mul_f32_e32 v77, 0x4b800000, v76
	v_cmp_gt_f32_e32 vcc, s6, v76
	s_nop 1
	v_cndmask_b32_e32 v76, v76, v77, vcc
	v_rsq_f32_e32 v80, v76
	v_lshl_add_u64 v[76:77], v[64:65], 0, v[134:135]
	v_lshl_add_u64 v[64:65], v[64:65], 0, v[112:113]
	v_mul_f32_e32 v82, 0x45800000, v80
	v_cndmask_b32_e32 v80, v80, v82, vcc
	v_pk_mul_f32 v[62:63], v[62:63], v[80:81] op_sel_hi:[1,0]
	v_pk_mul_f32 v[60:61], v[60:61], v[80:81] op_sel_hi:[1,0]
	v_pk_mul_f32 v[56:57], v[56:57], v[80:81] op_sel_hi:[1,0]
	global_store_dwordx4 v[68:69], v[60:63], off
	v_pk_mul_f32 v[58:59], v[58:59], v[80:81] op_sel_hi:[1,0]
	v_pk_mul_f32 v[52:53], v[52:53], v[80:81] op_sel_hi:[1,0]
	v_cvt_pk_bf16_f32 v60, v60, v61
	v_cvt_pk_bf16_f32 v61, v62, v63
	global_store_dwordx2 v[74:75], v[60:61], off
	global_store_dwordx4 v[70:71], v[56:59], off
	v_pk_mul_f32 v[54:55], v[54:55], v[80:81] op_sel_hi:[1,0]
	v_pk_mul_f32 v[48:49], v[48:49], v[80:81] op_sel_hi:[1,0]
	v_cvt_pk_bf16_f32 v56, v56, v57
	v_cvt_pk_bf16_f32 v57, v58, v59
	global_store_dwordx2 v[76:77], v[56:57], off
	global_store_dwordx4 v[72:73], v[52:55], off
	v_pk_mul_f32 v[50:51], v[50:51], v[80:81] op_sel_hi:[1,0]
	s_nop 0
	v_cvt_pk_bf16_f32 v52, v52, v53
	v_cvt_pk_bf16_f32 v53, v54, v55
	global_store_dwordx2 v[78:79], v[52:53], off
	global_store_dwordx4 v[66:67], v[48:51], off
	s_nop 1
	v_cvt_pk_bf16_f32 v48, v48, v49
	v_cvt_pk_bf16_f32 v49, v50, v51
	global_store_dwordx2 v[64:65], v[48:49], off
	global_load_dword v60, v[132:133], off offset:576
	v_mov_b32_e32 v49, v131
	v_add_u32_e32 v48, 0x90, v130
	v_lshlrev_b64 v[50:51], 12, v[48:49]
	v_and_or_b32 v48, v48, s7, v81
	v_ashrrev_i32_e32 v49, 31, v48
	v_lshlrev_b64 v[48:49], 9, v[48:49]
	v_lshl_add_u64 v[50:51], s[2:3], 0, v[50:51]
	v_lshl_add_u64 v[52:53], v[50:51], 0, v[146:147]
	v_lshl_add_u64 v[48:49], s[0:1], 0, v[48:49]
	v_lshl_add_u64 v[58:59], v[48:49], 0, v[138:139]
	v_lshl_add_u64 v[54:55], v[50:51], 0, v[144:145]
	v_lshl_add_u64 v[56:57], v[50:51], 0, v[142:143]
	v_lshl_add_u64 v[62:63], v[48:49], 0, v[136:137]
	v_lshl_add_u64 v[50:51], v[50:51], 0, v[140:141]
	s_waitcnt vmcnt(0)
	v_fmamk_f32 v60, v60, 0x3a800000, v148
	v_mul_f32_e32 v61, 0x4b800000, v60
	v_cmp_gt_f32_e32 vcc, s6, v60
	s_nop 1
	v_cndmask_b32_e32 v60, v60, v61, vcc
	v_rsq_f32_e32 v64, v60
	v_lshl_add_u64 v[60:61], v[48:49], 0, v[134:135]
	v_lshl_add_u64 v[48:49], v[48:49], 0, v[112:113]
	v_mul_f32_e32 v65, 0x45800000, v64
	v_cndmask_b32_e32 v64, v64, v65, vcc
	v_pk_mul_f32 v[46:47], v[46:47], v[64:65] op_sel_hi:[1,0]
	v_pk_mul_f32 v[44:45], v[44:45], v[64:65] op_sel_hi:[1,0]
	v_pk_mul_f32 v[40:41], v[40:41], v[64:65] op_sel_hi:[1,0]
	global_store_dwordx4 v[52:53], v[44:47], off
	v_pk_mul_f32 v[42:43], v[42:43], v[64:65] op_sel_hi:[1,0]
	v_pk_mul_f32 v[36:37], v[36:37], v[64:65] op_sel_hi:[1,0]
	v_cvt_pk_bf16_f32 v44, v44, v45
	v_cvt_pk_bf16_f32 v45, v46, v47
	global_store_dwordx2 v[58:59], v[44:45], off
	global_store_dwordx4 v[54:55], v[40:43], off
	v_pk_mul_f32 v[38:39], v[38:39], v[64:65] op_sel_hi:[1,0]
	v_pk_mul_f32 v[32:33], v[32:33], v[64:65] op_sel_hi:[1,0]
	v_cvt_pk_bf16_f32 v40, v40, v41
	v_cvt_pk_bf16_f32 v41, v42, v43
	global_store_dwordx2 v[60:61], v[40:41], off
	global_store_dwordx4 v[56:57], v[36:39], off
	v_pk_mul_f32 v[34:35], v[34:35], v[64:65] op_sel_hi:[1,0]
	s_nop 0
	v_cvt_pk_bf16_f32 v36, v36, v37
	v_cvt_pk_bf16_f32 v37, v38, v39
	global_store_dwordx2 v[62:63], v[36:37], off
	global_store_dwordx4 v[50:51], v[32:35], off
	s_nop 1
	v_cvt_pk_bf16_f32 v32, v32, v33
	v_cvt_pk_bf16_f32 v33, v34, v35
	global_store_dwordx2 v[48:49], v[32:33], off
	global_load_dword v44, v[132:133], off offset:640
	v_mov_b32_e32 v33, v131
	v_add_u32_e32 v32, 0xa0, v130
	v_lshlrev_b64 v[34:35], 12, v[32:33]
	v_and_or_b32 v32, v32, s8, v81
	v_ashrrev_i32_e32 v33, 31, v32
	v_lshlrev_b64 v[32:33], 9, v[32:33]
	v_lshl_add_u64 v[34:35], s[2:3], 0, v[34:35]
	v_lshl_add_u64 v[36:37], v[34:35], 0, v[146:147]
	v_lshl_add_u64 v[32:33], s[0:1], 0, v[32:33]
	v_lshl_add_u64 v[42:43], v[32:33], 0, v[138:139]
	v_lshl_add_u64 v[38:39], v[34:35], 0, v[144:145]
	v_lshl_add_u64 v[40:41], v[34:35], 0, v[142:143]
	v_lshl_add_u64 v[46:47], v[32:33], 0, v[136:137]
	v_lshl_add_u64 v[34:35], v[34:35], 0, v[140:141]
	v_add_u32_e32 v130, 0xb0, v130
	s_waitcnt vmcnt(0)
	v_fmamk_f32 v44, v44, 0x3a800000, v148
	v_mul_f32_e32 v45, 0x4b800000, v44
	v_cmp_gt_f32_e32 vcc, s6, v44
	s_nop 1
	v_cndmask_b32_e32 v44, v44, v45, vcc
	v_rsq_f32_e32 v48, v44
	v_lshl_add_u64 v[44:45], v[32:33], 0, v[134:135]
	v_lshl_add_u64 v[32:33], v[32:33], 0, v[112:113]
	v_mul_f32_e32 v49, 0x45800000, v48
	v_cndmask_b32_e32 v48, v48, v49, vcc
	v_pk_mul_f32 v[30:31], v[30:31], v[48:49] op_sel_hi:[1,0]
	v_pk_mul_f32 v[28:29], v[28:29], v[48:49] op_sel_hi:[1,0]
	v_pk_mul_f32 v[24:25], v[24:25], v[48:49] op_sel_hi:[1,0]
	global_store_dwordx4 v[36:37], v[28:31], off
	v_pk_mul_f32 v[26:27], v[26:27], v[48:49] op_sel_hi:[1,0]
	v_pk_mul_f32 v[20:21], v[20:21], v[48:49] op_sel_hi:[1,0]
	v_cvt_pk_bf16_f32 v28, v28, v29
	v_cvt_pk_bf16_f32 v29, v30, v31
	global_store_dwordx2 v[42:43], v[28:29], off
	global_store_dwordx4 v[38:39], v[24:27], off
	v_pk_mul_f32 v[22:23], v[22:23], v[48:49] op_sel_hi:[1,0]
	v_pk_mul_f32 v[16:17], v[16:17], v[48:49] op_sel_hi:[1,0]
	v_cvt_pk_bf16_f32 v24, v24, v25
	v_cvt_pk_bf16_f32 v25, v26, v27
	global_store_dwordx2 v[44:45], v[24:25], off
	global_store_dwordx4 v[40:41], v[20:23], off
	v_pk_mul_f32 v[18:19], v[18:19], v[48:49] op_sel_hi:[1,0]
	s_nop 0
	v_cvt_pk_bf16_f32 v20, v20, v21
	v_cvt_pk_bf16_f32 v21, v22, v23
	global_store_dwordx2 v[46:47], v[20:21], off
	global_store_dwordx4 v[34:35], v[16:19], off
	s_nop 1
	v_cvt_pk_bf16_f32 v16, v16, v17
	v_cvt_pk_bf16_f32 v17, v18, v19
	global_store_dwordx2 v[32:33], v[16:17], off
	global_load_dword v28, v[132:133], off offset:704
	v_and_or_b32 v18, v130, s4, v81
	v_lshlrev_b64 v[16:17], 12, v[130:131]
	v_ashrrev_i32_e32 v19, 31, v18
	v_lshlrev_b64 v[18:19], 9, v[18:19]
	v_lshl_add_u64 v[16:17], s[2:3], 0, v[16:17]
	v_lshl_add_u64 v[20:21], v[16:17], 0, v[146:147]
	v_lshl_add_u64 v[18:19], s[0:1], 0, v[18:19]
	v_lshl_add_u64 v[26:27], v[18:19], 0, v[138:139]
	v_lshl_add_u64 v[22:23], v[16:17], 0, v[144:145]
	v_lshl_add_u64 v[24:25], v[16:17], 0, v[142:143]
	v_lshl_add_u64 v[30:31], v[18:19], 0, v[136:137]
	v_lshl_add_u64 v[16:17], v[16:17], 0, v[140:141]
	s_waitcnt vmcnt(0)
	v_fmac_f32_e32 v148, 0x3a800000, v28
	v_mul_f32_e32 v28, 0x4b800000, v148
	v_cmp_gt_f32_e32 vcc, s6, v148
	s_nop 1
	v_cndmask_b32_e32 v28, v148, v28, vcc
	v_rsq_f32_e32 v32, v28
	v_lshl_add_u64 v[28:29], v[18:19], 0, v[134:135]
	v_lshl_add_u64 v[18:19], v[18:19], 0, v[112:113]
	v_mul_f32_e32 v33, 0x45800000, v32
	v_cndmask_b32_e32 v32, v32, v33, vcc
	v_pk_mul_f32 v[14:15], v[14:15], v[32:33] op_sel_hi:[1,0]
	v_pk_mul_f32 v[12:13], v[12:13], v[32:33] op_sel_hi:[1,0]
	v_pk_mul_f32 v[8:9], v[8:9], v[32:33] op_sel_hi:[1,0]
	global_store_dwordx4 v[20:21], v[12:15], off
	v_pk_mul_f32 v[10:11], v[10:11], v[32:33] op_sel_hi:[1,0]
	v_pk_mul_f32 v[4:5], v[4:5], v[32:33] op_sel_hi:[1,0]
	v_cvt_pk_bf16_f32 v12, v12, v13
	v_cvt_pk_bf16_f32 v13, v14, v15
	global_store_dwordx2 v[26:27], v[12:13], off
	global_store_dwordx4 v[22:23], v[8:11], off
	v_pk_mul_f32 v[6:7], v[6:7], v[32:33] op_sel_hi:[1,0]
	v_pk_mul_f32 v[0:1], v[0:1], v[32:33] op_sel_hi:[1,0]
	v_cvt_pk_bf16_f32 v8, v8, v9
	v_cvt_pk_bf16_f32 v9, v10, v11
	global_store_dwordx2 v[28:29], v[8:9], off
	global_store_dwordx4 v[24:25], v[4:7], off
	v_pk_mul_f32 v[2:3], v[2:3], v[32:33] op_sel_hi:[1,0]
	s_nop 0
	v_cvt_pk_bf16_f32 v4, v4, v5
	v_cvt_pk_bf16_f32 v5, v6, v7
	global_store_dwordx2 v[30:31], v[4:5], off
	global_store_dwordx4 v[16:17], v[0:3], off
	s_nop 1
	v_cvt_pk_bf16_f32 v0, v0, v1
	v_cvt_pk_bf16_f32 v1, v2, v3
	global_store_dwordx2 v[18:19], v[0:1], off
	s_waitcnt vmcnt(0)
	s_cbranch_scc0 .LBB0_440
	s_barrier

.LBB0_990:
	ds_read_b128 v[146:149], v155
	ds_read_b128 v[160:163], v155 offset:1024
	ds_read_b128 v[164:167], v155 offset:2048
	ds_read_b128 v[168:171], v155 offset:3072
	ds_read_b128 v[172:175], v156
	ds_read_b128 v[176:179], v156 offset:1024
	ds_read_b128 v[180:183], v156 offset:2048
	ds_read_b128 v[184:187], v156 offset:3072
	s_add_u32 s23, s54, 0xfffc0080
	s_addc_u32 s33, s55, -1
	s_cmp_eq_u32 s75, 12
	s_cselect_b32 s59, s20, s33
	s_cselect_b32 s58, s21, s23
	s_cselect_b32 s57, s19, s74
	s_cselect_b32 s56, s45, s73
	v_lshl_add_u64 v[220:221], s[54:55], 0, v[138:139]
	s_add_i32 m0, s51, 0xc000
	ds_read_b128 v[188:191], v157
	ds_read_b128 v[192:195], v157 offset:1024
	ds_read_b128 v[196:199], v157 offset:2048
	ds_read_b128 v[200:203], v157 offset:3072
	ds_read_b128 v[204:207], v157 offset:4096
	ds_read_b128 v[208:211], v157 offset:5120
	ds_read_b128 v[212:215], v157 offset:6144
	ds_read_b128 v[216:219], v157 offset:7168
	global_load_lds_dwordx4 v[220:221], off
	v_lshl_add_u64 v[220:221], s[54:55], 0, v[140:141]
	s_add_i32 m0, s51, 0xe000
	s_nop 0
	global_load_lds_dwordx4 v[220:221], off
	s_waitcnt vmcnt(8)
	s_waitcnt lgkmcnt(0)
	s_barrier
	s_setprio 1
	s_waitcnt lgkmcnt(0)
	v_mfma_f32_16x16x32_bf16 v[124:127], v[146:149], v[188:191], v[124:127]
	v_mfma_f32_16x16x32_bf16 v[120:123], v[164:167], v[188:191], v[120:123]
	v_mfma_f32_16x16x32_bf16 v[108:111], v[146:149], v[196:199], v[108:111]
	v_mfma_f32_16x16x32_bf16 v[104:107], v[164:167], v[196:199], v[104:107]
	v_mfma_f32_16x16x32_bf16 v[92:95], v[146:149], v[204:207], v[92:95]
	v_mfma_f32_16x16x32_bf16 v[88:91], v[164:167], v[204:207], v[88:91]
	v_mfma_f32_16x16x32_bf16 v[76:79], v[146:149], v[212:215], v[76:79]
	v_mfma_f32_16x16x32_bf16 v[72:75], v[164:167], v[212:215], v[72:75]
	v_mfma_f32_16x16x32_bf16 v[124:127], v[160:163], v[192:195], v[124:127]
	v_mfma_f32_16x16x32_bf16 v[120:123], v[168:171], v[192:195], v[120:123]
	v_mfma_f32_16x16x32_bf16 v[108:111], v[160:163], v[200:203], v[108:111]
	v_mfma_f32_16x16x32_bf16 v[104:107], v[168:171], v[200:203], v[104:107]
	v_mfma_f32_16x16x32_bf16 v[92:95], v[160:163], v[208:211], v[92:95]
	v_mfma_f32_16x16x32_bf16 v[88:91], v[168:171], v[208:211], v[88:91]
	v_mfma_f32_16x16x32_bf16 v[76:79], v[160:163], v[216:219], v[76:79]
	v_mfma_f32_16x16x32_bf16 v[72:75], v[168:171], v[216:219], v[72:75]
	v_mfma_f32_16x16x32_bf16 v[116:119], v[172:175], v[188:191], v[116:119]
	v_mfma_f32_16x16x32_bf16 v[112:115], v[180:183], v[188:191], v[112:115]
	v_mfma_f32_16x16x32_bf16 v[100:103], v[172:175], v[196:199], v[100:103]
	v_mfma_f32_16x16x32_bf16 v[96:99], v[180:183], v[196:199], v[96:99]
	v_mfma_f32_16x16x32_bf16 v[84:87], v[172:175], v[204:207], v[84:87]
	v_mfma_f32_16x16x32_bf16 v[80:83], v[180:183], v[204:207], v[80:83]
	v_mfma_f32_16x16x32_bf16 v[68:71], v[172:175], v[212:215], v[68:71]
	v_mfma_f32_16x16x32_bf16 v[64:67], v[180:183], v[212:215], v[64:67]
	v_mfma_f32_16x16x32_bf16 v[116:119], v[176:179], v[192:195], v[116:119]
	v_mfma_f32_16x16x32_bf16 v[112:115], v[184:187], v[192:195], v[112:115]
	v_mfma_f32_16x16x32_bf16 v[100:103], v[176:179], v[200:203], v[100:103]
	v_mfma_f32_16x16x32_bf16 v[96:99], v[184:187], v[200:203], v[96:99]
	v_mfma_f32_16x16x32_bf16 v[84:87], v[176:179], v[208:211], v[84:87]
	v_mfma_f32_16x16x32_bf16 v[80:83], v[184:187], v[208:211], v[80:83]
	v_mfma_f32_16x16x32_bf16 v[68:71], v[176:179], v[216:219], v[68:71]
	v_mfma_f32_16x16x32_bf16 v[64:67], v[184:187], v[216:219], v[64:67]
	s_setprio 0
	s_barrier
	s_add_i32 s23, s71, s62
	v_lshl_add_u64 v[220:221], s[56:57], 0, v[132:133]
	s_mov_b32 m0, s23
	ds_read_b128 v[188:191], v157 offset:16384
	ds_read_b128 v[192:195], v157 offset:17408
	ds_read_b128 v[196:199], v157 offset:18432
	ds_read_b128 v[200:203], v157 offset:19456
	ds_read_b128 v[204:207], v157 offset:20480
	ds_read_b128 v[208:211], v157 offset:21504
	ds_read_b128 v[212:215], v157 offset:22528
	ds_read_b128 v[216:219], v157 offset:23552
	global_load_lds_dwordx4 v[220:221], off
	s_add_i32 m0, s23, 0x2000
	s_add_u32 s76, s56, 0x40000
	v_lshl_add_u64 v[222:223], s[56:57], 0, v[136:137]
	s_addc_u32 s77, s57, 0
	s_add_i32 s23, s72, s62
	global_load_lds_dwordx4 v[222:223], off
	v_lshl_add_u64 v[224:225], s[76:77], 0, v[132:133]
	s_mov_b32 m0, s23
	v_lshl_add_u64 v[226:227], s[58:59], 0, v[134:135]
	global_load_lds_dwordx4 v[224:225], off
	v_lshl_add_u64 v[224:225], s[76:77], 0, v[136:137]
	s_add_i32 m0, s23, 0x2000
	s_nop 0
	global_load_lds_dwordx4 v[224:225], off
	v_lshl_add_u64 v[224:225], s[58:59], 0, v[130:131]
	s_mov_b32 m0, s51
	s_nop 0
	global_load_lds_dwordx4 v[224:225], off
	s_mov_b32 m0, s53
	s_nop 0
	global_load_lds_dwordx4 v[226:227], off
	s_waitcnt vmcnt(8)
	s_waitcnt lgkmcnt(0)
	s_barrier
	s_setprio 1
	s_waitcnt lgkmcnt(0)
	v_mfma_f32_16x16x32_bf16 v[60:63], v[146:149], v[188:191], v[60:63]
	v_mfma_f32_16x16x32_bf16 v[56:59], v[164:167], v[188:191], v[56:59]
	v_mfma_f32_16x16x32_bf16 v[44:47], v[146:149], v[196:199], v[44:47]
	v_mfma_f32_16x16x32_bf16 v[40:43], v[164:167], v[196:199], v[40:43]
	v_mfma_f32_16x16x32_bf16 v[28:31], v[146:149], v[204:207], v[28:31]
	v_mfma_f32_16x16x32_bf16 v[24:27], v[164:167], v[204:207], v[24:27]
	v_mfma_f32_16x16x32_bf16 v[12:15], v[146:149], v[212:215], v[12:15]
	v_mfma_f32_16x16x32_bf16 v[8:11], v[164:167], v[212:215], v[8:11]
	v_mfma_f32_16x16x32_bf16 v[60:63], v[160:163], v[192:195], v[60:63]
	v_mfma_f32_16x16x32_bf16 v[56:59], v[168:171], v[192:195], v[56:59]
	v_mfma_f32_16x16x32_bf16 v[44:47], v[160:163], v[200:203], v[44:47]
	v_mfma_f32_16x16x32_bf16 v[40:43], v[168:171], v[200:203], v[40:43]
	v_mfma_f32_16x16x32_bf16 v[28:31], v[160:163], v[208:211], v[28:31]
	v_mfma_f32_16x16x32_bf16 v[24:27], v[168:171], v[208:211], v[24:27]
	v_mfma_f32_16x16x32_bf16 v[12:15], v[160:163], v[216:219], v[12:15]
	v_mfma_f32_16x16x32_bf16 v[8:11], v[168:171], v[216:219], v[8:11]
	v_mfma_f32_16x16x32_bf16 v[52:55], v[172:175], v[188:191], v[52:55]
	v_mfma_f32_16x16x32_bf16 v[48:51], v[180:183], v[188:191], v[48:51]
	v_mfma_f32_16x16x32_bf16 v[36:39], v[172:175], v[196:199], v[36:39]
	v_mfma_f32_16x16x32_bf16 v[32:35], v[180:183], v[196:199], v[32:35]
	v_mfma_f32_16x16x32_bf16 v[20:23], v[172:175], v[204:207], v[20:23]
	v_mfma_f32_16x16x32_bf16 v[16:19], v[180:183], v[204:207], v[16:19]
	v_mfma_f32_16x16x32_bf16 v[4:7], v[172:175], v[212:215], v[4:7]
	v_mfma_f32_16x16x32_bf16 v[0:3], v[180:183], v[212:215], v[0:3]
	v_mfma_f32_16x16x32_bf16 v[52:55], v[176:179], v[192:195], v[52:55]
	v_mfma_f32_16x16x32_bf16 v[48:51], v[184:187], v[192:195], v[48:51]
	v_mfma_f32_16x16x32_bf16 v[36:39], v[176:179], v[200:203], v[36:39]
	v_mfma_f32_16x16x32_bf16 v[32:35], v[184:187], v[200:203], v[32:35]
	v_mfma_f32_16x16x32_bf16 v[20:23], v[176:179], v[208:211], v[20:23]
	v_mfma_f32_16x16x32_bf16 v[16:19], v[184:187], v[208:211], v[16:19]
	v_mfma_f32_16x16x32_bf16 v[4:7], v[176:179], v[216:219], v[4:7]
	v_mfma_f32_16x16x32_bf16 v[0:3], v[184:187], v[216:219], v[0:3]
	s_setprio 0
	s_barrier
	s_add_i32 s23, 0, 0x18000
	v_add_u32_e32 v159, s23, v153
	s_add_i32 s33, 0, 0x1c000
	ds_read_b128 v[146:149], v159
	ds_read_b128 v[160:163], v159 offset:1024
	ds_read_b128 v[164:167], v159 offset:2048
	ds_read_b128 v[168:171], v159 offset:3072
	v_add_u32_e32 v159, s33, v153
	ds_read_b128 v[172:175], v159
	ds_read_b128 v[176:179], v159 offset:1024
	ds_read_b128 v[180:183], v159 offset:2048
	ds_read_b128 v[184:187], v159 offset:3072
	s_add_u32 s58, s58, 0x40000
	s_addc_u32 s59, s59, 0
	s_mov_b32 m0, s63
	v_lshl_add_u64 v[228:229], s[58:59], 0, v[130:131]
	ds_read_b128 v[188:191], v157 offset:32768
	ds_read_b128 v[192:195], v157 offset:33792
	ds_read_b128 v[196:199], v157 offset:34816
	ds_read_b128 v[200:203], v157 offset:35840
	ds_read_b128 v[204:207], v157 offset:36864
	ds_read_b128 v[208:211], v157 offset:37888
	ds_read_b128 v[212:215], v157 offset:38912
	ds_read_b128 v[216:219], v157 offset:39936
	global_load_lds_dwordx4 v[228:229], off
	v_lshl_add_u64 v[228:229], s[58:59], 0, v[134:135]
	s_mov_b32 m0, s64
	s_nop 0
	global_load_lds_dwordx4 v[228:229], off
	s_waitcnt vmcnt(8)
	s_waitcnt lgkmcnt(0)
	s_barrier
	s_setprio 1
	s_waitcnt lgkmcnt(0)
	v_mfma_f32_16x16x32_bf16 v[124:127], v[146:149], v[188:191], v[124:127]
	v_mfma_f32_16x16x32_bf16 v[120:123], v[164:167], v[188:191], v[120:123]
	v_mfma_f32_16x16x32_bf16 v[108:111], v[146:149], v[196:199], v[108:111]
	v_mfma_f32_16x16x32_bf16 v[104:107], v[164:167], v[196:199], v[104:107]
	v_mfma_f32_16x16x32_bf16 v[92:95], v[146:149], v[204:207], v[92:95]
	v_mfma_f32_16x16x32_bf16 v[88:91], v[164:167], v[204:207], v[88:91]
	v_mfma_f32_16x16x32_bf16 v[76:79], v[146:149], v[212:215], v[76:79]
	v_mfma_f32_16x16x32_bf16 v[72:75], v[164:167], v[212:215], v[72:75]
	v_mfma_f32_16x16x32_bf16 v[124:127], v[160:163], v[192:195], v[124:127]
	v_mfma_f32_16x16x32_bf16 v[120:123], v[168:171], v[192:195], v[120:123]
	v_mfma_f32_16x16x32_bf16 v[108:111], v[160:163], v[200:203], v[108:111]
	v_mfma_f32_16x16x32_bf16 v[104:107], v[168:171], v[200:203], v[104:107]
	v_mfma_f32_16x16x32_bf16 v[92:95], v[160:163], v[208:211], v[92:95]
	v_mfma_f32_16x16x32_bf16 v[88:91], v[168:171], v[208:211], v[88:91]
	v_mfma_f32_16x16x32_bf16 v[76:79], v[160:163], v[216:219], v[76:79]
	v_mfma_f32_16x16x32_bf16 v[72:75], v[168:171], v[216:219], v[72:75]
	v_mfma_f32_16x16x32_bf16 v[116:119], v[172:175], v[188:191], v[116:119]
	v_mfma_f32_16x16x32_bf16 v[112:115], v[180:183], v[188:191], v[112:115]
	v_mfma_f32_16x16x32_bf16 v[100:103], v[172:175], v[196:199], v[100:103]
	v_mfma_f32_16x16x32_bf16 v[96:99], v[180:183], v[196:199], v[96:99]
	v_mfma_f32_16x16x32_bf16 v[84:87], v[172:175], v[204:207], v[84:87]
	v_mfma_f32_16x16x32_bf16 v[80:83], v[180:183], v[204:207], v[80:83]
	v_mfma_f32_16x16x32_bf16 v[68:71], v[172:175], v[212:215], v[68:71]
	v_mfma_f32_16x16x32_bf16 v[64:67], v[180:183], v[212:215], v[64:67]
	v_mfma_f32_16x16x32_bf16 v[116:119], v[176:179], v[192:195], v[116:119]
	v_mfma_f32_16x16x32_bf16 v[112:115], v[184:187], v[192:195], v[112:115]
	v_mfma_f32_16x16x32_bf16 v[100:103], v[176:179], v[200:203], v[100:103]
	v_mfma_f32_16x16x32_bf16 v[96:99], v[184:187], v[200:203], v[96:99]
	v_mfma_f32_16x16x32_bf16 v[84:87], v[176:179], v[208:211], v[84:87]
	v_mfma_f32_16x16x32_bf16 v[80:83], v[184:187], v[208:211], v[80:83]
	v_mfma_f32_16x16x32_bf16 v[68:71], v[176:179], v[216:219], v[68:71]
	v_mfma_f32_16x16x32_bf16 v[64:67], v[184:187], v[216:219], v[64:67]
	s_setprio 0
	s_barrier
	s_add_i32 s23, s23, s62
	v_lshl_add_u64 v[220:221], v[220:221], 0, s[14:15]
	s_mov_b32 m0, s23
	ds_read_b128 v[188:191], v157 offset:49152
	ds_read_b128 v[192:195], v157 offset:50176
	ds_read_b128 v[196:199], v157 offset:51200
	ds_read_b128 v[200:203], v157 offset:52224
	ds_read_b128 v[204:207], v157 offset:53248
	ds_read_b128 v[208:211], v157 offset:54272
	ds_read_b128 v[212:215], v157 offset:55296
	ds_read_b128 v[216:219], v157 offset:56320
	global_load_lds_dwordx4 v[220:221], off
	s_add_i32 m0, s23, 0x2000
	s_add_u32 s56, s56, 0x40080
	v_lshl_add_u64 v[220:221], v[222:223], 0, s[14:15]
	s_addc_u32 s57, s57, 0
	s_add_i32 s23, s33, s62
	global_load_lds_dwordx4 v[220:221], off
	v_lshl_add_u64 v[220:221], s[56:57], 0, v[132:133]
	s_mov_b32 m0, s23
	s_nop 0
	global_load_lds_dwordx4 v[220:221], off
	v_lshl_add_u64 v[220:221], s[56:57], 0, v[136:137]
	s_add_i32 m0, s23, 0x2000
	s_nop 0
	global_load_lds_dwordx4 v[220:221], off
	v_lshl_add_u64 v[220:221], v[224:225], 0, s[14:15]
	s_mov_b32 m0, s68
	s_nop 0
	global_load_lds_dwordx4 v[220:221], off
	v_lshl_add_u64 v[220:221], v[226:227], 0, s[14:15]
	s_mov_b32 m0, s69
	s_nop 0
	global_load_lds_dwordx4 v[220:221], off
	s_waitcnt vmcnt(8)
	s_waitcnt lgkmcnt(0)
	s_barrier
	s_setprio 1
	s_waitcnt lgkmcnt(0)
	v_mfma_f32_16x16x32_bf16 v[60:63], v[146:149], v[188:191], v[60:63]
	v_mfma_f32_16x16x32_bf16 v[56:59], v[164:167], v[188:191], v[56:59]
	v_mfma_f32_16x16x32_bf16 v[44:47], v[146:149], v[196:199], v[44:47]
	v_mfma_f32_16x16x32_bf16 v[40:43], v[164:167], v[196:199], v[40:43]
	v_mfma_f32_16x16x32_bf16 v[28:31], v[146:149], v[204:207], v[28:31]
	v_mfma_f32_16x16x32_bf16 v[24:27], v[164:167], v[204:207], v[24:27]
	v_mfma_f32_16x16x32_bf16 v[12:15], v[146:149], v[212:215], v[12:15]
	v_mfma_f32_16x16x32_bf16 v[8:11], v[164:167], v[212:215], v[8:11]
	v_mfma_f32_16x16x32_bf16 v[60:63], v[160:163], v[192:195], v[60:63]
	v_mfma_f32_16x16x32_bf16 v[56:59], v[168:171], v[192:195], v[56:59]
	v_mfma_f32_16x16x32_bf16 v[44:47], v[160:163], v[200:203], v[44:47]
	v_mfma_f32_16x16x32_bf16 v[40:43], v[168:171], v[200:203], v[40:43]
	v_mfma_f32_16x16x32_bf16 v[28:31], v[160:163], v[208:211], v[28:31]
	v_mfma_f32_16x16x32_bf16 v[24:27], v[168:171], v[208:211], v[24:27]
	v_mfma_f32_16x16x32_bf16 v[12:15], v[160:163], v[216:219], v[12:15]
	v_mfma_f32_16x16x32_bf16 v[8:11], v[168:171], v[216:219], v[8:11]
	v_mfma_f32_16x16x32_bf16 v[52:55], v[172:175], v[188:191], v[52:55]
	v_mfma_f32_16x16x32_bf16 v[48:51], v[180:183], v[188:191], v[48:51]
	v_mfma_f32_16x16x32_bf16 v[36:39], v[172:175], v[196:199], v[36:39]
	v_mfma_f32_16x16x32_bf16 v[32:35], v[180:183], v[196:199], v[32:35]
	v_mfma_f32_16x16x32_bf16 v[20:23], v[172:175], v[204:207], v[20:23]
	v_mfma_f32_16x16x32_bf16 v[16:19], v[180:183], v[204:207], v[16:19]
	v_mfma_f32_16x16x32_bf16 v[4:7], v[172:175], v[212:215], v[4:7]
	v_mfma_f32_16x16x32_bf16 v[0:3], v[180:183], v[212:215], v[0:3]
	v_mfma_f32_16x16x32_bf16 v[52:55], v[176:179], v[192:195], v[52:55]
	v_mfma_f32_16x16x32_bf16 v[48:51], v[184:187], v[192:195], v[48:51]
	v_mfma_f32_16x16x32_bf16 v[36:39], v[176:179], v[200:203], v[36:39]
	v_mfma_f32_16x16x32_bf16 v[32:35], v[184:187], v[200:203], v[32:35]
	v_mfma_f32_16x16x32_bf16 v[20:23], v[176:179], v[208:211], v[20:23]
	v_mfma_f32_16x16x32_bf16 v[16:19], v[184:187], v[208:211], v[16:19]
	v_mfma_f32_16x16x32_bf16 v[4:7], v[176:179], v[216:219], v[4:7]
	v_mfma_f32_16x16x32_bf16 v[0:3], v[184:187], v[216:219], v[0:3]
	s_setprio 0
	s_barrier
	s_add_i32 s75, s75, 2
	s_add_u32 s54, s54, 0x100
	s_addc_u32 s55, s55, 0
	s_add_u32 s73, s73, 0x100
	s_addc_u32 s74, s74, 0
	s_cmp_gt_u32 s75, 13
	s_cbranch_scc0 .LBB0_990
	s_and_b64 vcc, exec, s[16:17]
	s_cbranch_vccz .LBB0_993
	s_barrier

.LBB0_1086:
	ds_read_b128 v[146:149], v155
	ds_read_b128 v[160:163], v155 offset:1024
	ds_read_b128 v[164:167], v155 offset:2048
	ds_read_b128 v[168:171], v155 offset:3072
	ds_read_b128 v[172:175], v156
	ds_read_b128 v[176:179], v156 offset:1024
	ds_read_b128 v[180:183], v156 offset:2048
	ds_read_b128 v[184:187], v156 offset:3072
	s_add_u32 s23, s54, 0xfffc0080
	s_addc_u32 s33, s55, -1
	s_cmp_eq_u32 s82, 12
	s_cselect_b32 s59, s20, s33
	s_cselect_b32 s58, s21, s23
	s_cselect_b32 s57, s47, s81
	s_cselect_b32 s56, s49, s80
	v_lshl_add_u64 v[150:151], s[54:55], 0, v[138:139]
	s_add_i32 m0, s64, 0xc000
	ds_read_b128 v[188:191], v157
	ds_read_b128 v[192:195], v157 offset:1024
	ds_read_b128 v[196:199], v157 offset:2048
	ds_read_b128 v[200:203], v157 offset:3072
	ds_read_b128 v[204:207], v157 offset:4096
	ds_read_b128 v[208:211], v157 offset:5120
	ds_read_b128 v[212:215], v157 offset:6144
	ds_read_b128 v[216:219], v157 offset:7168
	global_load_lds_dwordx4 v[150:151], off
	v_lshl_add_u64 v[150:151], s[54:55], 0, v[140:141]
	s_add_i32 m0, s64, 0xe000
	s_nop 0
	global_load_lds_dwordx4 v[150:151], off
	s_waitcnt vmcnt(8)
	s_waitcnt lgkmcnt(0)
	s_barrier
	s_setprio 1
	s_waitcnt lgkmcnt(0)
	v_mfma_f32_16x16x32_bf16 v[124:127], v[146:149], v[188:191], v[124:127]
	v_mfma_f32_16x16x32_bf16 v[120:123], v[164:167], v[188:191], v[120:123]
	v_mfma_f32_16x16x32_bf16 v[108:111], v[146:149], v[196:199], v[108:111]
	v_mfma_f32_16x16x32_bf16 v[104:107], v[164:167], v[196:199], v[104:107]
	v_mfma_f32_16x16x32_bf16 v[92:95], v[146:149], v[204:207], v[92:95]
	v_mfma_f32_16x16x32_bf16 v[88:91], v[164:167], v[204:207], v[88:91]
	v_mfma_f32_16x16x32_bf16 v[76:79], v[146:149], v[212:215], v[76:79]
	v_mfma_f32_16x16x32_bf16 v[72:75], v[164:167], v[212:215], v[72:75]
	v_mfma_f32_16x16x32_bf16 v[124:127], v[160:163], v[192:195], v[124:127]
	v_mfma_f32_16x16x32_bf16 v[120:123], v[168:171], v[192:195], v[120:123]
	v_mfma_f32_16x16x32_bf16 v[108:111], v[160:163], v[200:203], v[108:111]
	v_mfma_f32_16x16x32_bf16 v[104:107], v[168:171], v[200:203], v[104:107]
	v_mfma_f32_16x16x32_bf16 v[92:95], v[160:163], v[208:211], v[92:95]
	v_mfma_f32_16x16x32_bf16 v[88:91], v[168:171], v[208:211], v[88:91]
	v_mfma_f32_16x16x32_bf16 v[76:79], v[160:163], v[216:219], v[76:79]
	v_mfma_f32_16x16x32_bf16 v[72:75], v[168:171], v[216:219], v[72:75]
	v_mfma_f32_16x16x32_bf16 v[116:119], v[172:175], v[188:191], v[116:119]
	v_mfma_f32_16x16x32_bf16 v[112:115], v[180:183], v[188:191], v[112:115]
	v_mfma_f32_16x16x32_bf16 v[100:103], v[172:175], v[196:199], v[100:103]
	v_mfma_f32_16x16x32_bf16 v[96:99], v[180:183], v[196:199], v[96:99]
	v_mfma_f32_16x16x32_bf16 v[84:87], v[172:175], v[204:207], v[84:87]
	v_mfma_f32_16x16x32_bf16 v[80:83], v[180:183], v[204:207], v[80:83]
	v_mfma_f32_16x16x32_bf16 v[68:71], v[172:175], v[212:215], v[68:71]
	v_mfma_f32_16x16x32_bf16 v[64:67], v[180:183], v[212:215], v[64:67]
	v_mfma_f32_16x16x32_bf16 v[116:119], v[176:179], v[192:195], v[116:119]
	v_mfma_f32_16x16x32_bf16 v[112:115], v[184:187], v[192:195], v[112:115]
	v_mfma_f32_16x16x32_bf16 v[100:103], v[176:179], v[200:203], v[100:103]
	v_mfma_f32_16x16x32_bf16 v[96:99], v[184:187], v[200:203], v[96:99]
	v_mfma_f32_16x16x32_bf16 v[84:87], v[176:179], v[208:211], v[84:87]
	v_mfma_f32_16x16x32_bf16 v[80:83], v[184:187], v[208:211], v[80:83]
	v_mfma_f32_16x16x32_bf16 v[68:71], v[176:179], v[216:219], v[68:71]
	v_mfma_f32_16x16x32_bf16 v[64:67], v[184:187], v[216:219], v[64:67]
	s_setprio 0
	s_barrier
	s_add_i32 s23, s73, s62
	v_lshl_add_u64 v[150:151], s[56:57], 0, v[132:133]
	s_mov_b32 m0, s23
	ds_read_b128 v[188:191], v157 offset:16384
	ds_read_b128 v[192:195], v157 offset:17408
	ds_read_b128 v[196:199], v157 offset:18432
	ds_read_b128 v[200:203], v157 offset:19456
	ds_read_b128 v[204:207], v157 offset:20480
	ds_read_b128 v[208:211], v157 offset:21504
	ds_read_b128 v[212:215], v157 offset:22528
	ds_read_b128 v[216:219], v157 offset:23552
	global_load_lds_dwordx4 v[150:151], off
	s_add_i32 m0, s23, 0x2000
	s_add_u32 s84, s56, 0x40000
	v_lshl_add_u64 v[220:221], s[56:57], 0, v[136:137]
	s_addc_u32 s85, s57, 0
	s_add_i32 s23, s74, s62
	global_load_lds_dwordx4 v[220:221], off
	v_lshl_add_u64 v[222:223], s[84:85], 0, v[132:133]
	s_mov_b32 m0, s23
	v_lshl_add_u64 v[224:225], s[58:59], 0, v[134:135]
	global_load_lds_dwordx4 v[222:223], off
	v_lshl_add_u64 v[222:223], s[84:85], 0, v[136:137]
	s_add_i32 m0, s23, 0x2000
	s_nop 0
	global_load_lds_dwordx4 v[222:223], off
	v_lshl_add_u64 v[222:223], s[58:59], 0, v[130:131]
	s_mov_b32 m0, s64
	s_nop 0
	global_load_lds_dwordx4 v[222:223], off
	s_mov_b32 m0, s65
	s_nop 0
	global_load_lds_dwordx4 v[224:225], off
	s_waitcnt vmcnt(8)
	s_waitcnt lgkmcnt(0)
	s_barrier
	s_setprio 1
	s_waitcnt lgkmcnt(0)
	v_mfma_f32_16x16x32_bf16 v[60:63], v[146:149], v[188:191], v[60:63]
	v_mfma_f32_16x16x32_bf16 v[56:59], v[164:167], v[188:191], v[56:59]
	v_mfma_f32_16x16x32_bf16 v[44:47], v[146:149], v[196:199], v[44:47]
	v_mfma_f32_16x16x32_bf16 v[40:43], v[164:167], v[196:199], v[40:43]
	v_mfma_f32_16x16x32_bf16 v[28:31], v[146:149], v[204:207], v[28:31]
	v_mfma_f32_16x16x32_bf16 v[24:27], v[164:167], v[204:207], v[24:27]
	v_mfma_f32_16x16x32_bf16 v[12:15], v[146:149], v[212:215], v[12:15]
	v_mfma_f32_16x16x32_bf16 v[8:11], v[164:167], v[212:215], v[8:11]
	v_mfma_f32_16x16x32_bf16 v[60:63], v[160:163], v[192:195], v[60:63]
	v_mfma_f32_16x16x32_bf16 v[56:59], v[168:171], v[192:195], v[56:59]
	v_mfma_f32_16x16x32_bf16 v[44:47], v[160:163], v[200:203], v[44:47]
	v_mfma_f32_16x16x32_bf16 v[40:43], v[168:171], v[200:203], v[40:43]
	v_mfma_f32_16x16x32_bf16 v[28:31], v[160:163], v[208:211], v[28:31]
	v_mfma_f32_16x16x32_bf16 v[24:27], v[168:171], v[208:211], v[24:27]
	v_mfma_f32_16x16x32_bf16 v[12:15], v[160:163], v[216:219], v[12:15]
	v_mfma_f32_16x16x32_bf16 v[8:11], v[168:171], v[216:219], v[8:11]
	v_mfma_f32_16x16x32_bf16 v[52:55], v[172:175], v[188:191], v[52:55]
	v_mfma_f32_16x16x32_bf16 v[48:51], v[180:183], v[188:191], v[48:51]
	v_mfma_f32_16x16x32_bf16 v[36:39], v[172:175], v[196:199], v[36:39]
	v_mfma_f32_16x16x32_bf16 v[32:35], v[180:183], v[196:199], v[32:35]
	v_mfma_f32_16x16x32_bf16 v[20:23], v[172:175], v[204:207], v[20:23]
	v_mfma_f32_16x16x32_bf16 v[16:19], v[180:183], v[204:207], v[16:19]
	v_mfma_f32_16x16x32_bf16 v[4:7], v[172:175], v[212:215], v[4:7]
	v_mfma_f32_16x16x32_bf16 v[0:3], v[180:183], v[212:215], v[0:3]
	v_mfma_f32_16x16x32_bf16 v[52:55], v[176:179], v[192:195], v[52:55]
	v_mfma_f32_16x16x32_bf16 v[48:51], v[184:187], v[192:195], v[48:51]
	v_mfma_f32_16x16x32_bf16 v[36:39], v[176:179], v[200:203], v[36:39]
	v_mfma_f32_16x16x32_bf16 v[32:35], v[184:187], v[200:203], v[32:35]
	v_mfma_f32_16x16x32_bf16 v[20:23], v[176:179], v[208:211], v[20:23]
	v_mfma_f32_16x16x32_bf16 v[16:19], v[184:187], v[208:211], v[16:19]
	v_mfma_f32_16x16x32_bf16 v[4:7], v[176:179], v[216:219], v[4:7]
	v_mfma_f32_16x16x32_bf16 v[0:3], v[184:187], v[216:219], v[0:3]
	s_setprio 0
	s_barrier
	s_add_i32 s23, 0, 0x18000
	v_add_u32_e32 v159, s23, v153
	s_add_i32 s33, 0, 0x1c000
	ds_read_b128 v[146:149], v159
	ds_read_b128 v[160:163], v159 offset:1024
	ds_read_b128 v[164:167], v159 offset:2048
	ds_read_b128 v[168:171], v159 offset:3072
	v_add_u32_e32 v159, s33, v153
	ds_read_b128 v[172:175], v159
	ds_read_b128 v[176:179], v159 offset:1024
	ds_read_b128 v[180:183], v159 offset:2048
	ds_read_b128 v[184:187], v159 offset:3072
	s_add_u32 s58, s58, 0x40000
	s_addc_u32 s59, s59, 0
	s_mov_b32 m0, s66
	v_lshl_add_u64 v[226:227], s[58:59], 0, v[130:131]
	ds_read_b128 v[188:191], v157 offset:32768
	ds_read_b128 v[192:195], v157 offset:33792
	ds_read_b128 v[196:199], v157 offset:34816
	ds_read_b128 v[200:203], v157 offset:35840
	ds_read_b128 v[204:207], v157 offset:36864
	ds_read_b128 v[208:211], v157 offset:37888
	ds_read_b128 v[212:215], v157 offset:38912
	ds_read_b128 v[216:219], v157 offset:39936
	global_load_lds_dwordx4 v[226:227], off
	v_lshl_add_u64 v[226:227], s[58:59], 0, v[134:135]
	s_mov_b32 m0, s67
	s_nop 0
	global_load_lds_dwordx4 v[226:227], off
	s_waitcnt vmcnt(8)
	s_waitcnt lgkmcnt(0)
	s_barrier
	s_setprio 1
	s_waitcnt lgkmcnt(0)
	v_mfma_f32_16x16x32_bf16 v[124:127], v[146:149], v[188:191], v[124:127]
	v_mfma_f32_16x16x32_bf16 v[120:123], v[164:167], v[188:191], v[120:123]
	v_mfma_f32_16x16x32_bf16 v[108:111], v[146:149], v[196:199], v[108:111]
	v_mfma_f32_16x16x32_bf16 v[104:107], v[164:167], v[196:199], v[104:107]
	v_mfma_f32_16x16x32_bf16 v[92:95], v[146:149], v[204:207], v[92:95]
	v_mfma_f32_16x16x32_bf16 v[88:91], v[164:167], v[204:207], v[88:91]
	v_mfma_f32_16x16x32_bf16 v[76:79], v[146:149], v[212:215], v[76:79]
	v_mfma_f32_16x16x32_bf16 v[72:75], v[164:167], v[212:215], v[72:75]
	v_mfma_f32_16x16x32_bf16 v[124:127], v[160:163], v[192:195], v[124:127]
	v_mfma_f32_16x16x32_bf16 v[120:123], v[168:171], v[192:195], v[120:123]
	v_mfma_f32_16x16x32_bf16 v[108:111], v[160:163], v[200:203], v[108:111]
	v_mfma_f32_16x16x32_bf16 v[104:107], v[168:171], v[200:203], v[104:107]
	v_mfma_f32_16x16x32_bf16 v[92:95], v[160:163], v[208:211], v[92:95]
	v_mfma_f32_16x16x32_bf16 v[88:91], v[168:171], v[208:211], v[88:91]
	v_mfma_f32_16x16x32_bf16 v[76:79], v[160:163], v[216:219], v[76:79]
	v_mfma_f32_16x16x32_bf16 v[72:75], v[168:171], v[216:219], v[72:75]
	v_mfma_f32_16x16x32_bf16 v[116:119], v[172:175], v[188:191], v[116:119]
	v_mfma_f32_16x16x32_bf16 v[112:115], v[180:183], v[188:191], v[112:115]
	v_mfma_f32_16x16x32_bf16 v[100:103], v[172:175], v[196:199], v[100:103]
	v_mfma_f32_16x16x32_bf16 v[96:99], v[180:183], v[196:199], v[96:99]
	v_mfma_f32_16x16x32_bf16 v[84:87], v[172:175], v[204:207], v[84:87]
	v_mfma_f32_16x16x32_bf16 v[80:83], v[180:183], v[204:207], v[80:83]
	v_mfma_f32_16x16x32_bf16 v[68:71], v[172:175], v[212:215], v[68:71]
	v_mfma_f32_16x16x32_bf16 v[64:67], v[180:183], v[212:215], v[64:67]
	v_mfma_f32_16x16x32_bf16 v[116:119], v[176:179], v[192:195], v[116:119]
	v_mfma_f32_16x16x32_bf16 v[112:115], v[184:187], v[192:195], v[112:115]
	v_mfma_f32_16x16x32_bf16 v[100:103], v[176:179], v[200:203], v[100:103]
	v_mfma_f32_16x16x32_bf16 v[96:99], v[184:187], v[200:203], v[96:99]
	v_mfma_f32_16x16x32_bf16 v[84:87], v[176:179], v[208:211], v[84:87]
	v_mfma_f32_16x16x32_bf16 v[80:83], v[184:187], v[208:211], v[80:83]
	v_mfma_f32_16x16x32_bf16 v[68:71], v[176:179], v[216:219], v[68:71]
	v_mfma_f32_16x16x32_bf16 v[64:67], v[184:187], v[216:219], v[64:67]
	s_setprio 0
	s_barrier
	s_add_i32 s23, s23, s62
	v_lshl_add_u64 v[150:151], v[150:151], 0, s[16:17]
	s_mov_b32 m0, s23
	ds_read_b128 v[188:191], v157 offset:49152
	ds_read_b128 v[192:195], v157 offset:50176
	ds_read_b128 v[196:199], v157 offset:51200
	ds_read_b128 v[200:203], v157 offset:52224
	ds_read_b128 v[204:207], v157 offset:53248
	ds_read_b128 v[208:211], v157 offset:54272
	ds_read_b128 v[212:215], v157 offset:55296
	ds_read_b128 v[216:219], v157 offset:56320
	global_load_lds_dwordx4 v[150:151], off
	s_add_i32 m0, s23, 0x2000
	s_add_u32 s56, s56, 0x40080
	v_lshl_add_u64 v[150:151], v[220:221], 0, s[16:17]
	s_addc_u32 s57, s57, 0
	s_add_i32 s23, s33, s62
	global_load_lds_dwordx4 v[150:151], off
	v_lshl_add_u64 v[150:151], s[56:57], 0, v[132:133]
	s_mov_b32 m0, s23
	s_nop 0
	global_load_lds_dwordx4 v[150:151], off
	v_lshl_add_u64 v[150:151], s[56:57], 0, v[136:137]
	s_add_i32 m0, s23, 0x2000
	s_nop 0
	global_load_lds_dwordx4 v[150:151], off
	v_lshl_add_u64 v[150:151], v[222:223], 0, s[16:17]
	s_mov_b32 m0, s70
	s_nop 0
	global_load_lds_dwordx4 v[150:151], off
	v_lshl_add_u64 v[150:151], v[224:225], 0, s[16:17]
	s_mov_b32 m0, s71
	s_nop 0
	global_load_lds_dwordx4 v[150:151], off
	s_waitcnt vmcnt(8)
	s_waitcnt lgkmcnt(0)
	s_barrier
	s_setprio 1
	s_waitcnt lgkmcnt(0)
	v_mfma_f32_16x16x32_bf16 v[60:63], v[146:149], v[188:191], v[60:63]
	v_mfma_f32_16x16x32_bf16 v[56:59], v[164:167], v[188:191], v[56:59]
	v_mfma_f32_16x16x32_bf16 v[44:47], v[146:149], v[196:199], v[44:47]
	v_mfma_f32_16x16x32_bf16 v[40:43], v[164:167], v[196:199], v[40:43]
	v_mfma_f32_16x16x32_bf16 v[28:31], v[146:149], v[204:207], v[28:31]
	v_mfma_f32_16x16x32_bf16 v[24:27], v[164:167], v[204:207], v[24:27]
	v_mfma_f32_16x16x32_bf16 v[12:15], v[146:149], v[212:215], v[12:15]
	v_mfma_f32_16x16x32_bf16 v[8:11], v[164:167], v[212:215], v[8:11]
	v_mfma_f32_16x16x32_bf16 v[60:63], v[160:163], v[192:195], v[60:63]
	v_mfma_f32_16x16x32_bf16 v[56:59], v[168:171], v[192:195], v[56:59]
	v_mfma_f32_16x16x32_bf16 v[44:47], v[160:163], v[200:203], v[44:47]
	v_mfma_f32_16x16x32_bf16 v[40:43], v[168:171], v[200:203], v[40:43]
	v_mfma_f32_16x16x32_bf16 v[28:31], v[160:163], v[208:211], v[28:31]
	v_mfma_f32_16x16x32_bf16 v[24:27], v[168:171], v[208:211], v[24:27]
	v_mfma_f32_16x16x32_bf16 v[12:15], v[160:163], v[216:219], v[12:15]
	v_mfma_f32_16x16x32_bf16 v[8:11], v[168:171], v[216:219], v[8:11]
	v_mfma_f32_16x16x32_bf16 v[52:55], v[172:175], v[188:191], v[52:55]
	v_mfma_f32_16x16x32_bf16 v[48:51], v[180:183], v[188:191], v[48:51]
	v_mfma_f32_16x16x32_bf16 v[36:39], v[172:175], v[196:199], v[36:39]
	v_mfma_f32_16x16x32_bf16 v[32:35], v[180:183], v[196:199], v[32:35]
	v_mfma_f32_16x16x32_bf16 v[20:23], v[172:175], v[204:207], v[20:23]
	v_mfma_f32_16x16x32_bf16 v[16:19], v[180:183], v[204:207], v[16:19]
	v_mfma_f32_16x16x32_bf16 v[4:7], v[172:175], v[212:215], v[4:7]
	v_mfma_f32_16x16x32_bf16 v[0:3], v[180:183], v[212:215], v[0:3]
	v_mfma_f32_16x16x32_bf16 v[52:55], v[176:179], v[192:195], v[52:55]
	v_mfma_f32_16x16x32_bf16 v[48:51], v[184:187], v[192:195], v[48:51]
	v_mfma_f32_16x16x32_bf16 v[36:39], v[176:179], v[200:203], v[36:39]
	v_mfma_f32_16x16x32_bf16 v[32:35], v[184:187], v[200:203], v[32:35]
	v_mfma_f32_16x16x32_bf16 v[20:23], v[176:179], v[208:211], v[20:23]
	v_mfma_f32_16x16x32_bf16 v[16:19], v[184:187], v[208:211], v[16:19]
	v_mfma_f32_16x16x32_bf16 v[4:7], v[176:179], v[216:219], v[4:7]
	v_mfma_f32_16x16x32_bf16 v[0:3], v[184:187], v[216:219], v[0:3]
	s_setprio 0
	s_barrier
	s_add_i32 s82, s82, 2
	s_add_u32 s54, s54, 0x100
	s_addc_u32 s55, s55, 0
	s_add_u32 s80, s80, 0x100
	s_addc_u32 s81, s81, 0
	s_cmp_gt_u32 s82, 13
	s_cbranch_scc0 .LBB0_1086
	s_and_b64 vcc, exec, s[18:19]
	s_cbranch_vccz .LBB0_1089
	s_barrier

.LBB0_1246:
	ds_read_b128 v[146:149], v155
	ds_read_b128 v[160:163], v155 offset:1024
	ds_read_b128 v[164:167], v155 offset:2048
	ds_read_b128 v[168:171], v155 offset:3072
	ds_read_b128 v[172:175], v156
	ds_read_b128 v[176:179], v156 offset:1024
	ds_read_b128 v[180:183], v156 offset:2048
	ds_read_b128 v[184:187], v156 offset:3072
	s_add_u32 s23, s46, 0xfffc0080
	s_addc_u32 s33, s47, -1
	s_cmp_eq_u32 s67, 12
	s_cselect_b32 s51, s20, s33
	s_cselect_b32 s50, s21, s23
	s_cselect_b32 s49, s19, s66
	s_cselect_b32 s48, s37, s65
	v_lshl_add_u64 v[220:221], s[46:47], 0, v[138:139]
	s_add_i32 m0, s43, 0xc000
	ds_read_b128 v[188:191], v157
	ds_read_b128 v[192:195], v157 offset:1024
	ds_read_b128 v[196:199], v157 offset:2048
	ds_read_b128 v[200:203], v157 offset:3072
	ds_read_b128 v[204:207], v157 offset:4096
	ds_read_b128 v[208:211], v157 offset:5120
	ds_read_b128 v[212:215], v157 offset:6144
	ds_read_b128 v[216:219], v157 offset:7168
	global_load_lds_dwordx4 v[220:221], off
	v_lshl_add_u64 v[220:221], s[46:47], 0, v[140:141]
	s_add_i32 m0, s43, 0xe000
	s_nop 0
	global_load_lds_dwordx4 v[220:221], off
	s_waitcnt vmcnt(8)
	s_waitcnt lgkmcnt(0)
	s_barrier
	s_setprio 1
	s_waitcnt lgkmcnt(0)
	v_mfma_f32_16x16x32_bf16 v[124:127], v[146:149], v[188:191], v[124:127]
	v_mfma_f32_16x16x32_bf16 v[120:123], v[164:167], v[188:191], v[120:123]
	v_mfma_f32_16x16x32_bf16 v[108:111], v[146:149], v[196:199], v[108:111]
	v_mfma_f32_16x16x32_bf16 v[104:107], v[164:167], v[196:199], v[104:107]
	v_mfma_f32_16x16x32_bf16 v[92:95], v[146:149], v[204:207], v[92:95]
	v_mfma_f32_16x16x32_bf16 v[88:91], v[164:167], v[204:207], v[88:91]
	v_mfma_f32_16x16x32_bf16 v[76:79], v[146:149], v[212:215], v[76:79]
	v_mfma_f32_16x16x32_bf16 v[72:75], v[164:167], v[212:215], v[72:75]
	v_mfma_f32_16x16x32_bf16 v[124:127], v[160:163], v[192:195], v[124:127]
	v_mfma_f32_16x16x32_bf16 v[120:123], v[168:171], v[192:195], v[120:123]
	v_mfma_f32_16x16x32_bf16 v[108:111], v[160:163], v[200:203], v[108:111]
	v_mfma_f32_16x16x32_bf16 v[104:107], v[168:171], v[200:203], v[104:107]
	v_mfma_f32_16x16x32_bf16 v[92:95], v[160:163], v[208:211], v[92:95]
	v_mfma_f32_16x16x32_bf16 v[88:91], v[168:171], v[208:211], v[88:91]
	v_mfma_f32_16x16x32_bf16 v[76:79], v[160:163], v[216:219], v[76:79]
	v_mfma_f32_16x16x32_bf16 v[72:75], v[168:171], v[216:219], v[72:75]
	v_mfma_f32_16x16x32_bf16 v[116:119], v[172:175], v[188:191], v[116:119]
	v_mfma_f32_16x16x32_bf16 v[112:115], v[180:183], v[188:191], v[112:115]
	v_mfma_f32_16x16x32_bf16 v[100:103], v[172:175], v[196:199], v[100:103]
	v_mfma_f32_16x16x32_bf16 v[96:99], v[180:183], v[196:199], v[96:99]
	v_mfma_f32_16x16x32_bf16 v[84:87], v[172:175], v[204:207], v[84:87]
	v_mfma_f32_16x16x32_bf16 v[80:83], v[180:183], v[204:207], v[80:83]
	v_mfma_f32_16x16x32_bf16 v[68:71], v[172:175], v[212:215], v[68:71]
	v_mfma_f32_16x16x32_bf16 v[64:67], v[180:183], v[212:215], v[64:67]
	v_mfma_f32_16x16x32_bf16 v[116:119], v[176:179], v[192:195], v[116:119]
	v_mfma_f32_16x16x32_bf16 v[112:115], v[184:187], v[192:195], v[112:115]
	v_mfma_f32_16x16x32_bf16 v[100:103], v[176:179], v[200:203], v[100:103]
	v_mfma_f32_16x16x32_bf16 v[96:99], v[184:187], v[200:203], v[96:99]
	v_mfma_f32_16x16x32_bf16 v[84:87], v[176:179], v[208:211], v[84:87]
	v_mfma_f32_16x16x32_bf16 v[80:83], v[184:187], v[208:211], v[80:83]
	v_mfma_f32_16x16x32_bf16 v[68:71], v[176:179], v[216:219], v[68:71]
	v_mfma_f32_16x16x32_bf16 v[64:67], v[184:187], v[216:219], v[64:67]
	s_setprio 0
	s_barrier
	s_add_i32 s23, s63, s54
	v_lshl_add_u64 v[220:221], s[48:49], 0, v[132:133]
	s_mov_b32 m0, s23
	ds_read_b128 v[188:191], v157 offset:16384
	ds_read_b128 v[192:195], v157 offset:17408
	ds_read_b128 v[196:199], v157 offset:18432
	ds_read_b128 v[200:203], v157 offset:19456
	ds_read_b128 v[204:207], v157 offset:20480
	ds_read_b128 v[208:211], v157 offset:21504
	ds_read_b128 v[212:215], v157 offset:22528
	ds_read_b128 v[216:219], v157 offset:23552
	global_load_lds_dwordx4 v[220:221], off
	s_add_i32 m0, s23, 0x2000
	s_add_u32 s68, s48, 0x40000
	v_lshl_add_u64 v[222:223], s[48:49], 0, v[136:137]
	s_addc_u32 s69, s49, 0
	s_add_i32 s23, s64, s54
	global_load_lds_dwordx4 v[222:223], off
	v_lshl_add_u64 v[224:225], s[68:69], 0, v[132:133]
	s_mov_b32 m0, s23
	v_lshl_add_u64 v[226:227], s[50:51], 0, v[134:135]
	global_load_lds_dwordx4 v[224:225], off
	v_lshl_add_u64 v[224:225], s[68:69], 0, v[136:137]
	s_add_i32 m0, s23, 0x2000
	s_nop 0
	global_load_lds_dwordx4 v[224:225], off
	v_lshl_add_u64 v[224:225], s[50:51], 0, v[130:131]
	s_mov_b32 m0, s43
	s_nop 0
	global_load_lds_dwordx4 v[224:225], off
	s_mov_b32 m0, s45
	s_nop 0
	global_load_lds_dwordx4 v[226:227], off
	s_waitcnt vmcnt(8)
	s_waitcnt lgkmcnt(0)
	s_barrier
	s_setprio 1
	s_waitcnt lgkmcnt(0)
	v_mfma_f32_16x16x32_bf16 v[60:63], v[146:149], v[188:191], v[60:63]
	v_mfma_f32_16x16x32_bf16 v[56:59], v[164:167], v[188:191], v[56:59]
	v_mfma_f32_16x16x32_bf16 v[44:47], v[146:149], v[196:199], v[44:47]
	v_mfma_f32_16x16x32_bf16 v[40:43], v[164:167], v[196:199], v[40:43]
	v_mfma_f32_16x16x32_bf16 v[28:31], v[146:149], v[204:207], v[28:31]
	v_mfma_f32_16x16x32_bf16 v[24:27], v[164:167], v[204:207], v[24:27]
	v_mfma_f32_16x16x32_bf16 v[12:15], v[146:149], v[212:215], v[12:15]
	v_mfma_f32_16x16x32_bf16 v[8:11], v[164:167], v[212:215], v[8:11]
	v_mfma_f32_16x16x32_bf16 v[60:63], v[160:163], v[192:195], v[60:63]
	v_mfma_f32_16x16x32_bf16 v[56:59], v[168:171], v[192:195], v[56:59]
	v_mfma_f32_16x16x32_bf16 v[44:47], v[160:163], v[200:203], v[44:47]
	v_mfma_f32_16x16x32_bf16 v[40:43], v[168:171], v[200:203], v[40:43]
	v_mfma_f32_16x16x32_bf16 v[28:31], v[160:163], v[208:211], v[28:31]
	v_mfma_f32_16x16x32_bf16 v[24:27], v[168:171], v[208:211], v[24:27]
	v_mfma_f32_16x16x32_bf16 v[12:15], v[160:163], v[216:219], v[12:15]
	v_mfma_f32_16x16x32_bf16 v[8:11], v[168:171], v[216:219], v[8:11]
	v_mfma_f32_16x16x32_bf16 v[52:55], v[172:175], v[188:191], v[52:55]
	v_mfma_f32_16x16x32_bf16 v[48:51], v[180:183], v[188:191], v[48:51]
	v_mfma_f32_16x16x32_bf16 v[36:39], v[172:175], v[196:199], v[36:39]
	v_mfma_f32_16x16x32_bf16 v[32:35], v[180:183], v[196:199], v[32:35]
	v_mfma_f32_16x16x32_bf16 v[20:23], v[172:175], v[204:207], v[20:23]
	v_mfma_f32_16x16x32_bf16 v[16:19], v[180:183], v[204:207], v[16:19]
	v_mfma_f32_16x16x32_bf16 v[4:7], v[172:175], v[212:215], v[4:7]
	v_mfma_f32_16x16x32_bf16 v[0:3], v[180:183], v[212:215], v[0:3]
	v_mfma_f32_16x16x32_bf16 v[52:55], v[176:179], v[192:195], v[52:55]
	v_mfma_f32_16x16x32_bf16 v[48:51], v[184:187], v[192:195], v[48:51]
	v_mfma_f32_16x16x32_bf16 v[36:39], v[176:179], v[200:203], v[36:39]
	v_mfma_f32_16x16x32_bf16 v[32:35], v[184:187], v[200:203], v[32:35]
	v_mfma_f32_16x16x32_bf16 v[20:23], v[176:179], v[208:211], v[20:23]
	v_mfma_f32_16x16x32_bf16 v[16:19], v[184:187], v[208:211], v[16:19]
	v_mfma_f32_16x16x32_bf16 v[4:7], v[176:179], v[216:219], v[4:7]
	v_mfma_f32_16x16x32_bf16 v[0:3], v[184:187], v[216:219], v[0:3]
	s_setprio 0
	s_barrier
	s_add_i32 s23, 0, 0x18000
	v_add_u32_e32 v159, s23, v153
	s_add_i32 s33, 0, 0x1c000
	ds_read_b128 v[146:149], v159
	ds_read_b128 v[160:163], v159 offset:1024
	ds_read_b128 v[164:167], v159 offset:2048
	ds_read_b128 v[168:171], v159 offset:3072
	v_add_u32_e32 v159, s33, v153
	ds_read_b128 v[172:175], v159
	ds_read_b128 v[176:179], v159 offset:1024
	ds_read_b128 v[180:183], v159 offset:2048
	ds_read_b128 v[184:187], v159 offset:3072
	s_add_u32 s50, s50, 0x40000
	s_addc_u32 s51, s51, 0
	s_mov_b32 m0, s55
	v_lshl_add_u64 v[228:229], s[50:51], 0, v[130:131]
	ds_read_b128 v[188:191], v157 offset:32768
	ds_read_b128 v[192:195], v157 offset:33792
	ds_read_b128 v[196:199], v157 offset:34816
	ds_read_b128 v[200:203], v157 offset:35840
	ds_read_b128 v[204:207], v157 offset:36864
	ds_read_b128 v[208:211], v157 offset:37888
	ds_read_b128 v[212:215], v157 offset:38912
	ds_read_b128 v[216:219], v157 offset:39936
	global_load_lds_dwordx4 v[228:229], off
	v_lshl_add_u64 v[228:229], s[50:51], 0, v[134:135]
	s_mov_b32 m0, s56
	s_nop 0
	global_load_lds_dwordx4 v[228:229], off
	s_waitcnt vmcnt(8)
	s_waitcnt lgkmcnt(0)
	s_barrier
	s_setprio 1
	s_waitcnt lgkmcnt(0)
	v_mfma_f32_16x16x32_bf16 v[124:127], v[146:149], v[188:191], v[124:127]
	v_mfma_f32_16x16x32_bf16 v[120:123], v[164:167], v[188:191], v[120:123]
	v_mfma_f32_16x16x32_bf16 v[108:111], v[146:149], v[196:199], v[108:111]
	v_mfma_f32_16x16x32_bf16 v[104:107], v[164:167], v[196:199], v[104:107]
	v_mfma_f32_16x16x32_bf16 v[92:95], v[146:149], v[204:207], v[92:95]
	v_mfma_f32_16x16x32_bf16 v[88:91], v[164:167], v[204:207], v[88:91]
	v_mfma_f32_16x16x32_bf16 v[76:79], v[146:149], v[212:215], v[76:79]
	v_mfma_f32_16x16x32_bf16 v[72:75], v[164:167], v[212:215], v[72:75]
	v_mfma_f32_16x16x32_bf16 v[124:127], v[160:163], v[192:195], v[124:127]
	v_mfma_f32_16x16x32_bf16 v[120:123], v[168:171], v[192:195], v[120:123]
	v_mfma_f32_16x16x32_bf16 v[108:111], v[160:163], v[200:203], v[108:111]
	v_mfma_f32_16x16x32_bf16 v[104:107], v[168:171], v[200:203], v[104:107]
	v_mfma_f32_16x16x32_bf16 v[92:95], v[160:163], v[208:211], v[92:95]
	v_mfma_f32_16x16x32_bf16 v[88:91], v[168:171], v[208:211], v[88:91]
	v_mfma_f32_16x16x32_bf16 v[76:79], v[160:163], v[216:219], v[76:79]
	v_mfma_f32_16x16x32_bf16 v[72:75], v[168:171], v[216:219], v[72:75]
	v_mfma_f32_16x16x32_bf16 v[116:119], v[172:175], v[188:191], v[116:119]
	v_mfma_f32_16x16x32_bf16 v[112:115], v[180:183], v[188:191], v[112:115]
	v_mfma_f32_16x16x32_bf16 v[100:103], v[172:175], v[196:199], v[100:103]
	v_mfma_f32_16x16x32_bf16 v[96:99], v[180:183], v[196:199], v[96:99]
	v_mfma_f32_16x16x32_bf16 v[84:87], v[172:175], v[204:207], v[84:87]
	v_mfma_f32_16x16x32_bf16 v[80:83], v[180:183], v[204:207], v[80:83]
	v_mfma_f32_16x16x32_bf16 v[68:71], v[172:175], v[212:215], v[68:71]
	v_mfma_f32_16x16x32_bf16 v[64:67], v[180:183], v[212:215], v[64:67]
	v_mfma_f32_16x16x32_bf16 v[116:119], v[176:179], v[192:195], v[116:119]
	v_mfma_f32_16x16x32_bf16 v[112:115], v[184:187], v[192:195], v[112:115]
	v_mfma_f32_16x16x32_bf16 v[100:103], v[176:179], v[200:203], v[100:103]
	v_mfma_f32_16x16x32_bf16 v[96:99], v[184:187], v[200:203], v[96:99]
	v_mfma_f32_16x16x32_bf16 v[84:87], v[176:179], v[208:211], v[84:87]
	v_mfma_f32_16x16x32_bf16 v[80:83], v[184:187], v[208:211], v[80:83]
	v_mfma_f32_16x16x32_bf16 v[68:71], v[176:179], v[216:219], v[68:71]
	v_mfma_f32_16x16x32_bf16 v[64:67], v[184:187], v[216:219], v[64:67]
	s_setprio 0
	s_barrier
	s_add_i32 s23, s23, s54
	v_lshl_add_u64 v[220:221], v[220:221], 0, s[14:15]
	s_mov_b32 m0, s23
	ds_read_b128 v[188:191], v157 offset:49152
	ds_read_b128 v[192:195], v157 offset:50176
	ds_read_b128 v[196:199], v157 offset:51200
	ds_read_b128 v[200:203], v157 offset:52224
	ds_read_b128 v[204:207], v157 offset:53248
	ds_read_b128 v[208:211], v157 offset:54272
	ds_read_b128 v[212:215], v157 offset:55296
	ds_read_b128 v[216:219], v157 offset:56320
	global_load_lds_dwordx4 v[220:221], off
	s_add_i32 m0, s23, 0x2000
	s_add_u32 s48, s48, 0x40080
	v_lshl_add_u64 v[220:221], v[222:223], 0, s[14:15]
	s_addc_u32 s49, s49, 0
	s_add_i32 s23, s33, s54
	global_load_lds_dwordx4 v[220:221], off
	v_lshl_add_u64 v[220:221], s[48:49], 0, v[132:133]
	s_mov_b32 m0, s23
	s_nop 0
	global_load_lds_dwordx4 v[220:221], off
	v_lshl_add_u64 v[220:221], s[48:49], 0, v[136:137]
	s_add_i32 m0, s23, 0x2000
	s_nop 0
	global_load_lds_dwordx4 v[220:221], off
	v_lshl_add_u64 v[220:221], v[224:225], 0, s[14:15]
	s_mov_b32 m0, s60
	s_nop 0
	global_load_lds_dwordx4 v[220:221], off
	v_lshl_add_u64 v[220:221], v[226:227], 0, s[14:15]
	s_mov_b32 m0, s61
	s_nop 0
	global_load_lds_dwordx4 v[220:221], off
	s_waitcnt vmcnt(8)
	s_waitcnt lgkmcnt(0)
	s_barrier
	s_setprio 1
	s_waitcnt lgkmcnt(0)
	v_mfma_f32_16x16x32_bf16 v[60:63], v[146:149], v[188:191], v[60:63]
	v_mfma_f32_16x16x32_bf16 v[56:59], v[164:167], v[188:191], v[56:59]
	v_mfma_f32_16x16x32_bf16 v[44:47], v[146:149], v[196:199], v[44:47]
	v_mfma_f32_16x16x32_bf16 v[40:43], v[164:167], v[196:199], v[40:43]
	v_mfma_f32_16x16x32_bf16 v[28:31], v[146:149], v[204:207], v[28:31]
	v_mfma_f32_16x16x32_bf16 v[24:27], v[164:167], v[204:207], v[24:27]
	v_mfma_f32_16x16x32_bf16 v[12:15], v[146:149], v[212:215], v[12:15]
	v_mfma_f32_16x16x32_bf16 v[8:11], v[164:167], v[212:215], v[8:11]
	v_mfma_f32_16x16x32_bf16 v[60:63], v[160:163], v[192:195], v[60:63]
	v_mfma_f32_16x16x32_bf16 v[56:59], v[168:171], v[192:195], v[56:59]
	v_mfma_f32_16x16x32_bf16 v[44:47], v[160:163], v[200:203], v[44:47]
	v_mfma_f32_16x16x32_bf16 v[40:43], v[168:171], v[200:203], v[40:43]
	v_mfma_f32_16x16x32_bf16 v[28:31], v[160:163], v[208:211], v[28:31]
	v_mfma_f32_16x16x32_bf16 v[24:27], v[168:171], v[208:211], v[24:27]
	v_mfma_f32_16x16x32_bf16 v[12:15], v[160:163], v[216:219], v[12:15]
	v_mfma_f32_16x16x32_bf16 v[8:11], v[168:171], v[216:219], v[8:11]
	v_mfma_f32_16x16x32_bf16 v[52:55], v[172:175], v[188:191], v[52:55]
	v_mfma_f32_16x16x32_bf16 v[48:51], v[180:183], v[188:191], v[48:51]
	v_mfma_f32_16x16x32_bf16 v[36:39], v[172:175], v[196:199], v[36:39]
	v_mfma_f32_16x16x32_bf16 v[32:35], v[180:183], v[196:199], v[32:35]
	v_mfma_f32_16x16x32_bf16 v[20:23], v[172:175], v[204:207], v[20:23]
	v_mfma_f32_16x16x32_bf16 v[16:19], v[180:183], v[204:207], v[16:19]
	v_mfma_f32_16x16x32_bf16 v[4:7], v[172:175], v[212:215], v[4:7]
	v_mfma_f32_16x16x32_bf16 v[0:3], v[180:183], v[212:215], v[0:3]
	v_mfma_f32_16x16x32_bf16 v[52:55], v[176:179], v[192:195], v[52:55]
	v_mfma_f32_16x16x32_bf16 v[48:51], v[184:187], v[192:195], v[48:51]
	v_mfma_f32_16x16x32_bf16 v[36:39], v[176:179], v[200:203], v[36:39]
	v_mfma_f32_16x16x32_bf16 v[32:35], v[184:187], v[200:203], v[32:35]
	v_mfma_f32_16x16x32_bf16 v[20:23], v[176:179], v[208:211], v[20:23]
	v_mfma_f32_16x16x32_bf16 v[16:19], v[184:187], v[208:211], v[16:19]
	v_mfma_f32_16x16x32_bf16 v[4:7], v[176:179], v[216:219], v[4:7]
	v_mfma_f32_16x16x32_bf16 v[0:3], v[184:187], v[216:219], v[0:3]
	s_setprio 0
	s_barrier
	s_add_i32 s67, s67, 2
	s_add_u32 s46, s46, 0x100
	s_addc_u32 s47, s47, 0
	s_add_u32 s65, s65, 0x100
	s_addc_u32 s66, s66, 0
	s_cmp_gt_u32 s67, 13
	s_cbranch_scc0 .LBB0_1246
	s_and_b64 vcc, exec, s[16:17]
	s_cbranch_vccz .LBB0_1249
	s_barrier

.LBB0_1342:
	ds_read_b128 v[146:149], v154
	ds_read_b128 v[158:161], v154 offset:1024
	ds_read_b128 v[162:165], v154 offset:2048
	ds_read_b128 v[166:169], v154 offset:3072
	ds_read_b128 v[170:173], v155
	ds_read_b128 v[174:177], v155 offset:1024
	ds_read_b128 v[178:181], v155 offset:2048
	ds_read_b128 v[182:185], v155 offset:3072
	s_add_u32 s23, s40, 0xfffc0080
	s_addc_u32 s33, s41, -1
	s_cmp_eq_u32 s67, 12
	s_cselect_b32 s45, s19, s33
	s_cselect_b32 s44, s20, s23
	s_cselect_b32 s43, s17, s66
	s_cselect_b32 s42, s21, s65
	v_lshl_add_u64 v[218:219], s[40:41], 0, v[138:139]
	s_add_i32 m0, s52, 0xc000
	ds_read_b128 v[186:189], v156
	ds_read_b128 v[190:193], v156 offset:1024
	ds_read_b128 v[194:197], v156 offset:2048
	ds_read_b128 v[198:201], v156 offset:3072
	ds_read_b128 v[202:205], v156 offset:4096
	ds_read_b128 v[206:209], v156 offset:5120
	ds_read_b128 v[210:213], v156 offset:6144
	ds_read_b128 v[214:217], v156 offset:7168
	global_load_lds_dwordx4 v[218:219], off
	v_lshl_add_u64 v[218:219], s[40:41], 0, v[140:141]
	s_add_i32 m0, s52, 0xe000
	s_nop 0
	global_load_lds_dwordx4 v[218:219], off
	s_waitcnt vmcnt(8)
	s_waitcnt lgkmcnt(0)
	s_barrier
	s_setprio 1
	s_waitcnt lgkmcnt(0)
	v_mfma_f32_16x16x32_bf16 v[116:119], v[146:149], v[186:189], v[116:119]
	v_mfma_f32_16x16x32_bf16 v[112:115], v[162:165], v[186:189], v[112:115]
	v_mfma_f32_16x16x32_bf16 v[100:103], v[146:149], v[194:197], v[100:103]
	v_mfma_f32_16x16x32_bf16 v[96:99], v[162:165], v[194:197], v[96:99]
	v_mfma_f32_16x16x32_bf16 v[84:87], v[146:149], v[202:205], v[84:87]
	v_mfma_f32_16x16x32_bf16 v[80:83], v[162:165], v[202:205], v[80:83]
	v_mfma_f32_16x16x32_bf16 v[72:75], v[146:149], v[210:213], v[72:75]
	v_mfma_f32_16x16x32_bf16 v[64:67], v[162:165], v[210:213], v[64:67]
	v_mfma_f32_16x16x32_bf16 v[116:119], v[158:161], v[190:193], v[116:119]
	v_mfma_f32_16x16x32_bf16 v[112:115], v[166:169], v[190:193], v[112:115]
	v_mfma_f32_16x16x32_bf16 v[100:103], v[158:161], v[198:201], v[100:103]
	v_mfma_f32_16x16x32_bf16 v[96:99], v[166:169], v[198:201], v[96:99]
	v_mfma_f32_16x16x32_bf16 v[84:87], v[158:161], v[206:209], v[84:87]
	v_mfma_f32_16x16x32_bf16 v[80:83], v[166:169], v[206:209], v[80:83]
	v_mfma_f32_16x16x32_bf16 v[72:75], v[158:161], v[214:217], v[72:75]
	v_mfma_f32_16x16x32_bf16 v[64:67], v[166:169], v[214:217], v[64:67]
	v_mfma_f32_16x16x32_bf16 v[124:127], v[170:173], v[186:189], v[124:127]
	v_mfma_f32_16x16x32_bf16 v[120:123], v[178:181], v[186:189], v[120:123]
	v_mfma_f32_16x16x32_bf16 v[108:111], v[170:173], v[194:197], v[108:111]
	v_mfma_f32_16x16x32_bf16 v[104:107], v[178:181], v[194:197], v[104:107]
	v_mfma_f32_16x16x32_bf16 v[92:95], v[170:173], v[202:205], v[92:95]
	v_mfma_f32_16x16x32_bf16 v[88:91], v[178:181], v[202:205], v[88:91]
	v_mfma_f32_16x16x32_bf16 v[76:79], v[170:173], v[210:213], v[76:79]
	v_mfma_f32_16x16x32_bf16 v[68:71], v[178:181], v[210:213], v[68:71]
	v_mfma_f32_16x16x32_bf16 v[124:127], v[174:177], v[190:193], v[124:127]
	v_mfma_f32_16x16x32_bf16 v[120:123], v[182:185], v[190:193], v[120:123]
	v_mfma_f32_16x16x32_bf16 v[108:111], v[174:177], v[198:201], v[108:111]
	v_mfma_f32_16x16x32_bf16 v[104:107], v[182:185], v[198:201], v[104:107]
	v_mfma_f32_16x16x32_bf16 v[92:95], v[174:177], v[206:209], v[92:95]
	v_mfma_f32_16x16x32_bf16 v[88:91], v[182:185], v[206:209], v[88:91]
	v_mfma_f32_16x16x32_bf16 v[76:79], v[174:177], v[214:217], v[76:79]
	v_mfma_f32_16x16x32_bf16 v[68:71], v[182:185], v[214:217], v[68:71]
	s_setprio 0
	s_barrier
	s_add_i32 s23, s61, s50
	v_lshl_add_u64 v[218:219], s[42:43], 0, v[132:133]
	s_mov_b32 m0, s23
	ds_read_b128 v[186:189], v156 offset:16384
	ds_read_b128 v[190:193], v156 offset:17408
	ds_read_b128 v[194:197], v156 offset:18432
	ds_read_b128 v[198:201], v156 offset:19456
	ds_read_b128 v[202:205], v156 offset:20480
	ds_read_b128 v[206:209], v156 offset:21504
	ds_read_b128 v[210:213], v156 offset:22528
	ds_read_b128 v[214:217], v156 offset:23552
	global_load_lds_dwordx4 v[218:219], off
	s_add_i32 m0, s23, 0x2000
	s_add_u32 s68, s42, 0x40000
	v_lshl_add_u64 v[220:221], s[42:43], 0, v[136:137]
	s_addc_u32 s69, s43, 0
	s_add_i32 s23, s62, s50
	global_load_lds_dwordx4 v[220:221], off
	v_lshl_add_u64 v[222:223], s[68:69], 0, v[132:133]
	s_mov_b32 m0, s23
	v_lshl_add_u64 v[224:225], s[44:45], 0, v[134:135]
	global_load_lds_dwordx4 v[222:223], off
	v_lshl_add_u64 v[222:223], s[68:69], 0, v[136:137]
	s_add_i32 m0, s23, 0x2000
	s_nop 0
	global_load_lds_dwordx4 v[222:223], off
	v_lshl_add_u64 v[222:223], s[44:45], 0, v[130:131]
	s_mov_b32 m0, s52
	s_nop 0
	global_load_lds_dwordx4 v[222:223], off
	s_mov_b32 m0, s53
	s_nop 0
	global_load_lds_dwordx4 v[224:225], off
	s_waitcnt vmcnt(8)
	s_waitcnt lgkmcnt(0)
	s_barrier
	s_setprio 1
	s_waitcnt lgkmcnt(0)
	v_mfma_f32_16x16x32_bf16 v[56:59], v[146:149], v[186:189], v[56:59]
	v_mfma_f32_16x16x32_bf16 v[48:51], v[162:165], v[186:189], v[48:51]
	v_mfma_f32_16x16x32_bf16 v[40:43], v[146:149], v[194:197], v[40:43]
	v_mfma_f32_16x16x32_bf16 v[32:35], v[162:165], v[194:197], v[32:35]
	v_mfma_f32_16x16x32_bf16 v[24:27], v[146:149], v[202:205], v[24:27]
	v_mfma_f32_16x16x32_bf16 v[16:19], v[162:165], v[202:205], v[16:19]
	v_mfma_f32_16x16x32_bf16 v[8:11], v[146:149], v[210:213], v[8:11]
	v_mfma_f32_16x16x32_bf16 v[0:3], v[162:165], v[210:213], v[0:3]
	v_mfma_f32_16x16x32_bf16 v[56:59], v[158:161], v[190:193], v[56:59]
	v_mfma_f32_16x16x32_bf16 v[48:51], v[166:169], v[190:193], v[48:51]
	v_mfma_f32_16x16x32_bf16 v[40:43], v[158:161], v[198:201], v[40:43]
	v_mfma_f32_16x16x32_bf16 v[32:35], v[166:169], v[198:201], v[32:35]
	v_mfma_f32_16x16x32_bf16 v[24:27], v[158:161], v[206:209], v[24:27]
	v_mfma_f32_16x16x32_bf16 v[16:19], v[166:169], v[206:209], v[16:19]
	v_mfma_f32_16x16x32_bf16 v[8:11], v[158:161], v[214:217], v[8:11]
	v_mfma_f32_16x16x32_bf16 v[0:3], v[166:169], v[214:217], v[0:3]
	v_mfma_f32_16x16x32_bf16 v[60:63], v[170:173], v[186:189], v[60:63]
	v_mfma_f32_16x16x32_bf16 v[52:55], v[178:181], v[186:189], v[52:55]
	v_mfma_f32_16x16x32_bf16 v[44:47], v[170:173], v[194:197], v[44:47]
	v_mfma_f32_16x16x32_bf16 v[36:39], v[178:181], v[194:197], v[36:39]
	v_mfma_f32_16x16x32_bf16 v[28:31], v[170:173], v[202:205], v[28:31]
	v_mfma_f32_16x16x32_bf16 v[20:23], v[178:181], v[202:205], v[20:23]
	v_mfma_f32_16x16x32_bf16 v[12:15], v[170:173], v[210:213], v[12:15]
	v_mfma_f32_16x16x32_bf16 v[4:7], v[178:181], v[210:213], v[4:7]
	v_mfma_f32_16x16x32_bf16 v[60:63], v[174:177], v[190:193], v[60:63]
	v_mfma_f32_16x16x32_bf16 v[52:55], v[182:185], v[190:193], v[52:55]
	v_mfma_f32_16x16x32_bf16 v[44:47], v[174:177], v[198:201], v[44:47]
	v_mfma_f32_16x16x32_bf16 v[36:39], v[182:185], v[198:201], v[36:39]
	v_mfma_f32_16x16x32_bf16 v[28:31], v[174:177], v[206:209], v[28:31]
	v_mfma_f32_16x16x32_bf16 v[20:23], v[182:185], v[206:209], v[20:23]
	v_mfma_f32_16x16x32_bf16 v[12:15], v[174:177], v[214:217], v[12:15]
	v_mfma_f32_16x16x32_bf16 v[4:7], v[182:185], v[214:217], v[4:7]
	s_setprio 0
	s_barrier
	s_add_i32 s23, 0, 0x18000
	s_add_i32 s33, 0, 0x1c000
	v_add_u32_e32 v166, s23, v152
	v_add_u32_e32 v182, s33, v152
	ds_read_b128 v[146:149], v166
	ds_read_b128 v[158:161], v166 offset:1024
	ds_read_b128 v[162:165], v166 offset:2048
	ds_read_b128 v[166:169], v166 offset:3072
	ds_read_b128 v[170:173], v182
	ds_read_b128 v[174:177], v182 offset:1024
	ds_read_b128 v[178:181], v182 offset:2048
	ds_read_b128 v[182:185], v182 offset:3072
	s_add_u32 s44, s44, 0x40000
	s_addc_u32 s45, s45, 0
	s_mov_b32 m0, s54
	v_lshl_add_u64 v[226:227], s[44:45], 0, v[130:131]
	ds_read_b128 v[186:189], v156 offset:32768
	ds_read_b128 v[190:193], v156 offset:33792
	ds_read_b128 v[194:197], v156 offset:34816
	ds_read_b128 v[198:201], v156 offset:35840
	ds_read_b128 v[202:205], v156 offset:36864
	ds_read_b128 v[206:209], v156 offset:37888
	ds_read_b128 v[210:213], v156 offset:38912
	ds_read_b128 v[214:217], v156 offset:39936
	global_load_lds_dwordx4 v[226:227], off
	v_lshl_add_u64 v[226:227], s[44:45], 0, v[134:135]
	s_mov_b32 m0, s55
	s_nop 0
	global_load_lds_dwordx4 v[226:227], off
	s_waitcnt vmcnt(8)
	s_waitcnt lgkmcnt(0)
	s_barrier
	s_setprio 1
	s_waitcnt lgkmcnt(0)
	v_mfma_f32_16x16x32_bf16 v[116:119], v[146:149], v[186:189], v[116:119]
	v_mfma_f32_16x16x32_bf16 v[112:115], v[162:165], v[186:189], v[112:115]
	v_mfma_f32_16x16x32_bf16 v[100:103], v[146:149], v[194:197], v[100:103]
	v_mfma_f32_16x16x32_bf16 v[96:99], v[162:165], v[194:197], v[96:99]
	v_mfma_f32_16x16x32_bf16 v[84:87], v[146:149], v[202:205], v[84:87]
	v_mfma_f32_16x16x32_bf16 v[80:83], v[162:165], v[202:205], v[80:83]
	v_mfma_f32_16x16x32_bf16 v[72:75], v[146:149], v[210:213], v[72:75]
	v_mfma_f32_16x16x32_bf16 v[64:67], v[162:165], v[210:213], v[64:67]
	v_mfma_f32_16x16x32_bf16 v[116:119], v[158:161], v[190:193], v[116:119]
	v_mfma_f32_16x16x32_bf16 v[112:115], v[166:169], v[190:193], v[112:115]
	v_mfma_f32_16x16x32_bf16 v[100:103], v[158:161], v[198:201], v[100:103]
	v_mfma_f32_16x16x32_bf16 v[96:99], v[166:169], v[198:201], v[96:99]
	v_mfma_f32_16x16x32_bf16 v[84:87], v[158:161], v[206:209], v[84:87]
	v_mfma_f32_16x16x32_bf16 v[80:83], v[166:169], v[206:209], v[80:83]
	v_mfma_f32_16x16x32_bf16 v[72:75], v[158:161], v[214:217], v[72:75]
	v_mfma_f32_16x16x32_bf16 v[64:67], v[166:169], v[214:217], v[64:67]
	v_mfma_f32_16x16x32_bf16 v[124:127], v[170:173], v[186:189], v[124:127]
	v_mfma_f32_16x16x32_bf16 v[120:123], v[178:181], v[186:189], v[120:123]
	v_mfma_f32_16x16x32_bf16 v[108:111], v[170:173], v[194:197], v[108:111]
	v_mfma_f32_16x16x32_bf16 v[104:107], v[178:181], v[194:197], v[104:107]
	v_mfma_f32_16x16x32_bf16 v[92:95], v[170:173], v[202:205], v[92:95]
	v_mfma_f32_16x16x32_bf16 v[88:91], v[178:181], v[202:205], v[88:91]
	v_mfma_f32_16x16x32_bf16 v[76:79], v[170:173], v[210:213], v[76:79]
	v_mfma_f32_16x16x32_bf16 v[68:71], v[178:181], v[210:213], v[68:71]
	v_mfma_f32_16x16x32_bf16 v[124:127], v[174:177], v[190:193], v[124:127]
	v_mfma_f32_16x16x32_bf16 v[120:123], v[182:185], v[190:193], v[120:123]
	v_mfma_f32_16x16x32_bf16 v[108:111], v[174:177], v[198:201], v[108:111]
	v_mfma_f32_16x16x32_bf16 v[104:107], v[182:185], v[198:201], v[104:107]
	v_mfma_f32_16x16x32_bf16 v[92:95], v[174:177], v[206:209], v[92:95]
	v_mfma_f32_16x16x32_bf16 v[88:91], v[182:185], v[206:209], v[88:91]
	v_mfma_f32_16x16x32_bf16 v[76:79], v[174:177], v[214:217], v[76:79]
	v_mfma_f32_16x16x32_bf16 v[68:71], v[182:185], v[214:217], v[68:71]
	s_setprio 0
	s_barrier
	s_add_i32 s23, s23, s50
	v_lshl_add_u64 v[218:219], v[218:219], 0, s[12:13]
	s_mov_b32 m0, s23
	ds_read_b128 v[186:189], v156 offset:49152
	ds_read_b128 v[190:193], v156 offset:50176
	ds_read_b128 v[194:197], v156 offset:51200
	ds_read_b128 v[198:201], v156 offset:52224
	ds_read_b128 v[202:205], v156 offset:53248
	ds_read_b128 v[206:209], v156 offset:54272
	ds_read_b128 v[210:213], v156 offset:55296
	ds_read_b128 v[214:217], v156 offset:56320
	global_load_lds_dwordx4 v[218:219], off
	s_add_i32 m0, s23, 0x2000
	s_add_u32 s42, s42, 0x40080
	v_lshl_add_u64 v[218:219], v[220:221], 0, s[12:13]
	s_addc_u32 s43, s43, 0
	s_add_i32 s23, s33, s50
	global_load_lds_dwordx4 v[218:219], off
	v_lshl_add_u64 v[218:219], s[42:43], 0, v[132:133]
	s_mov_b32 m0, s23
	s_nop 0
	global_load_lds_dwordx4 v[218:219], off
	v_lshl_add_u64 v[218:219], s[42:43], 0, v[136:137]
	s_add_i32 m0, s23, 0x2000
	s_nop 0
	global_load_lds_dwordx4 v[218:219], off
	v_lshl_add_u64 v[218:219], v[222:223], 0, s[12:13]
	s_mov_b32 m0, s58
	s_nop 0
	global_load_lds_dwordx4 v[218:219], off
	v_lshl_add_u64 v[218:219], v[224:225], 0, s[12:13]
	s_mov_b32 m0, s59
	s_nop 0
	global_load_lds_dwordx4 v[218:219], off
	s_waitcnt vmcnt(8)
	s_waitcnt lgkmcnt(0)
	s_barrier
	s_setprio 1
	s_waitcnt lgkmcnt(0)
	v_mfma_f32_16x16x32_bf16 v[56:59], v[146:149], v[186:189], v[56:59]
	v_mfma_f32_16x16x32_bf16 v[48:51], v[162:165], v[186:189], v[48:51]
	v_mfma_f32_16x16x32_bf16 v[40:43], v[146:149], v[194:197], v[40:43]
	v_mfma_f32_16x16x32_bf16 v[32:35], v[162:165], v[194:197], v[32:35]
	v_mfma_f32_16x16x32_bf16 v[24:27], v[146:149], v[202:205], v[24:27]
	v_mfma_f32_16x16x32_bf16 v[16:19], v[162:165], v[202:205], v[16:19]
	v_mfma_f32_16x16x32_bf16 v[8:11], v[146:149], v[210:213], v[8:11]
	v_mfma_f32_16x16x32_bf16 v[0:3], v[162:165], v[210:213], v[0:3]
	v_mfma_f32_16x16x32_bf16 v[56:59], v[158:161], v[190:193], v[56:59]
	v_mfma_f32_16x16x32_bf16 v[48:51], v[166:169], v[190:193], v[48:51]
	v_mfma_f32_16x16x32_bf16 v[40:43], v[158:161], v[198:201], v[40:43]
	v_mfma_f32_16x16x32_bf16 v[32:35], v[166:169], v[198:201], v[32:35]
	v_mfma_f32_16x16x32_bf16 v[24:27], v[158:161], v[206:209], v[24:27]
	v_mfma_f32_16x16x32_bf16 v[16:19], v[166:169], v[206:209], v[16:19]
	v_mfma_f32_16x16x32_bf16 v[8:11], v[158:161], v[214:217], v[8:11]
	v_mfma_f32_16x16x32_bf16 v[0:3], v[166:169], v[214:217], v[0:3]
	v_mfma_f32_16x16x32_bf16 v[60:63], v[170:173], v[186:189], v[60:63]
	v_mfma_f32_16x16x32_bf16 v[52:55], v[178:181], v[186:189], v[52:55]
	v_mfma_f32_16x16x32_bf16 v[44:47], v[170:173], v[194:197], v[44:47]
	v_mfma_f32_16x16x32_bf16 v[36:39], v[178:181], v[194:197], v[36:39]
	v_mfma_f32_16x16x32_bf16 v[28:31], v[170:173], v[202:205], v[28:31]
	v_mfma_f32_16x16x32_bf16 v[20:23], v[178:181], v[202:205], v[20:23]
	v_mfma_f32_16x16x32_bf16 v[12:15], v[170:173], v[210:213], v[12:15]
	v_mfma_f32_16x16x32_bf16 v[4:7], v[178:181], v[210:213], v[4:7]
	v_mfma_f32_16x16x32_bf16 v[60:63], v[174:177], v[190:193], v[60:63]
	v_mfma_f32_16x16x32_bf16 v[52:55], v[182:185], v[190:193], v[52:55]
	v_mfma_f32_16x16x32_bf16 v[44:47], v[174:177], v[198:201], v[44:47]
	v_mfma_f32_16x16x32_bf16 v[36:39], v[182:185], v[198:201], v[36:39]
	v_mfma_f32_16x16x32_bf16 v[28:31], v[174:177], v[206:209], v[28:31]
	v_mfma_f32_16x16x32_bf16 v[20:23], v[182:185], v[206:209], v[20:23]
	v_mfma_f32_16x16x32_bf16 v[12:15], v[174:177], v[214:217], v[12:15]
	v_mfma_f32_16x16x32_bf16 v[4:7], v[182:185], v[214:217], v[4:7]
	s_setprio 0
	s_barrier
	s_add_i32 s67, s67, 2
	s_add_u32 s40, s40, 0x100
	s_addc_u32 s41, s41, 0
	s_add_u32 s65, s65, 0x100
	s_addc_u32 s66, s66, 0
	s_cmp_gt_u32 s67, 13
	s_cbranch_scc0 .LBB0_1342
	s_and_b64 vcc, exec, s[14:15]
	s_cbranch_vccz .LBB0_1345
	s_barrier

.LBB0_1424:
	ds_read_b128 v[146:149], v156
	ds_read_b128 v[160:163], v156 offset:1024
	ds_read_b128 v[164:167], v156 offset:2048
	ds_read_b128 v[168:171], v156 offset:3072
	ds_read_b128 v[172:175], v157
	ds_read_b128 v[176:179], v157 offset:1024
	ds_read_b128 v[180:183], v157 offset:2048
	ds_read_b128 v[184:187], v157 offset:3072
	s_add_u32 s23, s38, 0xfff50080
	s_addc_u32 s33, s39, -1
	s_cmp_eq_u32 s65, 40
	s_cselect_b32 s43, s1, s33
	s_cselect_b32 s42, s0, s23
	s_cselect_b32 s41, s37, s64
	s_cselect_b32 s40, s36, s63
	v_lshl_add_u64 v[220:221], s[38:39], 0, v[138:139]
	s_add_i32 m0, s49, 0xc000
	ds_read_b128 v[188:191], v158
	ds_read_b128 v[192:195], v158 offset:1024
	ds_read_b128 v[196:199], v158 offset:2048
	ds_read_b128 v[200:203], v158 offset:3072
	ds_read_b128 v[204:207], v158 offset:4096
	ds_read_b128 v[208:211], v158 offset:5120
	ds_read_b128 v[212:215], v158 offset:6144
	ds_read_b128 v[216:219], v158 offset:7168
	global_load_lds_dwordx4 v[220:221], off
	v_lshl_add_u64 v[220:221], s[38:39], 0, v[140:141]
	s_add_i32 m0, s49, 0xe000
	s_nop 0
	global_load_lds_dwordx4 v[220:221], off
	s_waitcnt vmcnt(8)
	s_waitcnt lgkmcnt(0)
	s_barrier
	s_setprio 1
	s_waitcnt lgkmcnt(0)
	v_mfma_f32_16x16x32_bf16 v[124:127], v[146:149], v[188:191], v[124:127]
	v_mfma_f32_16x16x32_bf16 v[120:123], v[164:167], v[188:191], v[120:123]
	v_mfma_f32_16x16x32_bf16 v[108:111], v[146:149], v[196:199], v[108:111]
	v_mfma_f32_16x16x32_bf16 v[104:107], v[164:167], v[196:199], v[104:107]
	v_mfma_f32_16x16x32_bf16 v[92:95], v[146:149], v[204:207], v[92:95]
	v_mfma_f32_16x16x32_bf16 v[88:91], v[164:167], v[204:207], v[88:91]
	v_mfma_f32_16x16x32_bf16 v[76:79], v[146:149], v[212:215], v[76:79]
	v_mfma_f32_16x16x32_bf16 v[72:75], v[164:167], v[212:215], v[72:75]
	v_mfma_f32_16x16x32_bf16 v[124:127], v[160:163], v[192:195], v[124:127]
	v_mfma_f32_16x16x32_bf16 v[120:123], v[168:171], v[192:195], v[120:123]
	v_mfma_f32_16x16x32_bf16 v[108:111], v[160:163], v[200:203], v[108:111]
	v_mfma_f32_16x16x32_bf16 v[104:107], v[168:171], v[200:203], v[104:107]
	v_mfma_f32_16x16x32_bf16 v[92:95], v[160:163], v[208:211], v[92:95]
	v_mfma_f32_16x16x32_bf16 v[88:91], v[168:171], v[208:211], v[88:91]
	v_mfma_f32_16x16x32_bf16 v[76:79], v[160:163], v[216:219], v[76:79]
	v_mfma_f32_16x16x32_bf16 v[72:75], v[168:171], v[216:219], v[72:75]
	v_mfma_f32_16x16x32_bf16 v[116:119], v[172:175], v[188:191], v[116:119]
	v_mfma_f32_16x16x32_bf16 v[112:115], v[180:183], v[188:191], v[112:115]
	v_mfma_f32_16x16x32_bf16 v[100:103], v[172:175], v[196:199], v[100:103]
	v_mfma_f32_16x16x32_bf16 v[96:99], v[180:183], v[196:199], v[96:99]
	v_mfma_f32_16x16x32_bf16 v[84:87], v[172:175], v[204:207], v[84:87]
	v_mfma_f32_16x16x32_bf16 v[80:83], v[180:183], v[204:207], v[80:83]
	v_mfma_f32_16x16x32_bf16 v[68:71], v[172:175], v[212:215], v[68:71]
	v_mfma_f32_16x16x32_bf16 v[64:67], v[180:183], v[212:215], v[64:67]
	v_mfma_f32_16x16x32_bf16 v[116:119], v[176:179], v[192:195], v[116:119]
	v_mfma_f32_16x16x32_bf16 v[112:115], v[184:187], v[192:195], v[112:115]
	v_mfma_f32_16x16x32_bf16 v[100:103], v[176:179], v[200:203], v[100:103]
	v_mfma_f32_16x16x32_bf16 v[96:99], v[184:187], v[200:203], v[96:99]
	v_mfma_f32_16x16x32_bf16 v[84:87], v[176:179], v[208:211], v[84:87]
	v_mfma_f32_16x16x32_bf16 v[80:83], v[184:187], v[208:211], v[80:83]
	v_mfma_f32_16x16x32_bf16 v[68:71], v[176:179], v[216:219], v[68:71]
	v_mfma_f32_16x16x32_bf16 v[64:67], v[184:187], v[216:219], v[64:67]
	s_setprio 0
	s_barrier
	s_add_i32 s23, s59, s48
	v_lshl_add_u64 v[220:221], s[40:41], 0, v[132:133]
	s_mov_b32 m0, s23
	ds_read_b128 v[188:191], v158 offset:16384
	ds_read_b128 v[192:195], v158 offset:17408
	ds_read_b128 v[196:199], v158 offset:18432
	ds_read_b128 v[200:203], v158 offset:19456
	ds_read_b128 v[204:207], v158 offset:20480
	ds_read_b128 v[208:211], v158 offset:21504
	ds_read_b128 v[212:215], v158 offset:22528
	ds_read_b128 v[216:219], v158 offset:23552
	global_load_lds_dwordx4 v[220:221], off
	s_add_i32 m0, s23, 0x2000
	s_add_u32 s66, s40, 0xb0000
	v_lshl_add_u64 v[222:223], s[40:41], 0, v[136:137]
	s_addc_u32 s67, s41, 0
	s_add_i32 s23, s60, s48
	global_load_lds_dwordx4 v[222:223], off
	v_lshl_add_u64 v[224:225], s[66:67], 0, v[132:133]
	s_mov_b32 m0, s23
	v_lshl_add_u64 v[226:227], s[42:43], 0, v[134:135]
	global_load_lds_dwordx4 v[224:225], off
	v_lshl_add_u64 v[224:225], s[66:67], 0, v[136:137]
	s_add_i32 m0, s23, 0x2000
	s_nop 0
	global_load_lds_dwordx4 v[224:225], off
	v_lshl_add_u64 v[224:225], s[42:43], 0, v[130:131]
	s_mov_b32 m0, s49
	s_nop 0
	global_load_lds_dwordx4 v[224:225], off
	s_mov_b32 m0, s50
	s_nop 0
	global_load_lds_dwordx4 v[226:227], off
	s_waitcnt vmcnt(8)
	s_waitcnt lgkmcnt(0)
	s_barrier
	s_setprio 1
	s_waitcnt lgkmcnt(0)
	v_mfma_f32_16x16x32_bf16 v[60:63], v[146:149], v[188:191], v[60:63]
	v_mfma_f32_16x16x32_bf16 v[56:59], v[164:167], v[188:191], v[56:59]
	v_mfma_f32_16x16x32_bf16 v[44:47], v[146:149], v[196:199], v[44:47]
	v_mfma_f32_16x16x32_bf16 v[40:43], v[164:167], v[196:199], v[40:43]
	v_mfma_f32_16x16x32_bf16 v[28:31], v[146:149], v[204:207], v[28:31]
	v_mfma_f32_16x16x32_bf16 v[24:27], v[164:167], v[204:207], v[24:27]
	v_mfma_f32_16x16x32_bf16 v[12:15], v[146:149], v[212:215], v[12:15]
	v_mfma_f32_16x16x32_bf16 v[8:11], v[164:167], v[212:215], v[8:11]
	v_mfma_f32_16x16x32_bf16 v[60:63], v[160:163], v[192:195], v[60:63]
	v_mfma_f32_16x16x32_bf16 v[56:59], v[168:171], v[192:195], v[56:59]
	v_mfma_f32_16x16x32_bf16 v[44:47], v[160:163], v[200:203], v[44:47]
	v_mfma_f32_16x16x32_bf16 v[40:43], v[168:171], v[200:203], v[40:43]
	v_mfma_f32_16x16x32_bf16 v[28:31], v[160:163], v[208:211], v[28:31]
	v_mfma_f32_16x16x32_bf16 v[24:27], v[168:171], v[208:211], v[24:27]
	v_mfma_f32_16x16x32_bf16 v[12:15], v[160:163], v[216:219], v[12:15]
	v_mfma_f32_16x16x32_bf16 v[8:11], v[168:171], v[216:219], v[8:11]
	v_mfma_f32_16x16x32_bf16 v[52:55], v[172:175], v[188:191], v[52:55]
	v_mfma_f32_16x16x32_bf16 v[48:51], v[180:183], v[188:191], v[48:51]
	v_mfma_f32_16x16x32_bf16 v[36:39], v[172:175], v[196:199], v[36:39]
	v_mfma_f32_16x16x32_bf16 v[32:35], v[180:183], v[196:199], v[32:35]
	v_mfma_f32_16x16x32_bf16 v[20:23], v[172:175], v[204:207], v[20:23]
	v_mfma_f32_16x16x32_bf16 v[16:19], v[180:183], v[204:207], v[16:19]
	v_mfma_f32_16x16x32_bf16 v[4:7], v[172:175], v[212:215], v[4:7]
	v_mfma_f32_16x16x32_bf16 v[0:3], v[180:183], v[212:215], v[0:3]
	v_mfma_f32_16x16x32_bf16 v[52:55], v[176:179], v[192:195], v[52:55]
	v_mfma_f32_16x16x32_bf16 v[48:51], v[184:187], v[192:195], v[48:51]
	v_mfma_f32_16x16x32_bf16 v[36:39], v[176:179], v[200:203], v[36:39]
	v_mfma_f32_16x16x32_bf16 v[32:35], v[184:187], v[200:203], v[32:35]
	v_mfma_f32_16x16x32_bf16 v[20:23], v[176:179], v[208:211], v[20:23]
	v_mfma_f32_16x16x32_bf16 v[16:19], v[184:187], v[208:211], v[16:19]
	v_mfma_f32_16x16x32_bf16 v[4:7], v[176:179], v[216:219], v[4:7]
	v_mfma_f32_16x16x32_bf16 v[0:3], v[184:187], v[216:219], v[0:3]
	s_setprio 0
	s_barrier
	s_add_i32 s23, 0, 0x18000
	s_add_i32 s33, 0, 0x1c000
	v_add_u32_e32 v168, s23, v154
	v_add_u32_e32 v184, s33, v154
	ds_read_b128 v[146:149], v168
	ds_read_b128 v[160:163], v168 offset:1024
	ds_read_b128 v[164:167], v168 offset:2048
	ds_read_b128 v[168:171], v168 offset:3072
	ds_read_b128 v[172:175], v184
	ds_read_b128 v[176:179], v184 offset:1024
	ds_read_b128 v[180:183], v184 offset:2048
	ds_read_b128 v[184:187], v184 offset:3072
	s_add_u32 s42, s42, 0xb0000
	s_addc_u32 s43, s43, 0
	s_mov_b32 m0, s51
	v_lshl_add_u64 v[228:229], s[42:43], 0, v[130:131]
	ds_read_b128 v[188:191], v158 offset:32768
	ds_read_b128 v[192:195], v158 offset:33792
	ds_read_b128 v[196:199], v158 offset:34816
	ds_read_b128 v[200:203], v158 offset:35840
	ds_read_b128 v[204:207], v158 offset:36864
	ds_read_b128 v[208:211], v158 offset:37888
	ds_read_b128 v[212:215], v158 offset:38912
	ds_read_b128 v[216:219], v158 offset:39936
	global_load_lds_dwordx4 v[228:229], off
	v_lshl_add_u64 v[228:229], s[42:43], 0, v[134:135]
	s_mov_b32 m0, s52
	s_nop 0
	global_load_lds_dwordx4 v[228:229], off
	s_waitcnt vmcnt(8)
	s_waitcnt lgkmcnt(0)
	s_barrier
	s_setprio 1
	s_waitcnt lgkmcnt(0)
	v_mfma_f32_16x16x32_bf16 v[124:127], v[146:149], v[188:191], v[124:127]
	v_mfma_f32_16x16x32_bf16 v[120:123], v[164:167], v[188:191], v[120:123]
	v_mfma_f32_16x16x32_bf16 v[108:111], v[146:149], v[196:199], v[108:111]
	v_mfma_f32_16x16x32_bf16 v[104:107], v[164:167], v[196:199], v[104:107]
	v_mfma_f32_16x16x32_bf16 v[92:95], v[146:149], v[204:207], v[92:95]
	v_mfma_f32_16x16x32_bf16 v[88:91], v[164:167], v[204:207], v[88:91]
	v_mfma_f32_16x16x32_bf16 v[76:79], v[146:149], v[212:215], v[76:79]
	v_mfma_f32_16x16x32_bf16 v[72:75], v[164:167], v[212:215], v[72:75]
	v_mfma_f32_16x16x32_bf16 v[124:127], v[160:163], v[192:195], v[124:127]
	v_mfma_f32_16x16x32_bf16 v[120:123], v[168:171], v[192:195], v[120:123]
	v_mfma_f32_16x16x32_bf16 v[108:111], v[160:163], v[200:203], v[108:111]
	v_mfma_f32_16x16x32_bf16 v[104:107], v[168:171], v[200:203], v[104:107]
	v_mfma_f32_16x16x32_bf16 v[92:95], v[160:163], v[208:211], v[92:95]
	v_mfma_f32_16x16x32_bf16 v[88:91], v[168:171], v[208:211], v[88:91]
	v_mfma_f32_16x16x32_bf16 v[76:79], v[160:163], v[216:219], v[76:79]
	v_mfma_f32_16x16x32_bf16 v[72:75], v[168:171], v[216:219], v[72:75]
	v_mfma_f32_16x16x32_bf16 v[116:119], v[172:175], v[188:191], v[116:119]
	v_mfma_f32_16x16x32_bf16 v[112:115], v[180:183], v[188:191], v[112:115]
	v_mfma_f32_16x16x32_bf16 v[100:103], v[172:175], v[196:199], v[100:103]
	v_mfma_f32_16x16x32_bf16 v[96:99], v[180:183], v[196:199], v[96:99]
	v_mfma_f32_16x16x32_bf16 v[84:87], v[172:175], v[204:207], v[84:87]
	v_mfma_f32_16x16x32_bf16 v[80:83], v[180:183], v[204:207], v[80:83]
	v_mfma_f32_16x16x32_bf16 v[68:71], v[172:175], v[212:215], v[68:71]
	v_mfma_f32_16x16x32_bf16 v[64:67], v[180:183], v[212:215], v[64:67]
	v_mfma_f32_16x16x32_bf16 v[116:119], v[176:179], v[192:195], v[116:119]
	v_mfma_f32_16x16x32_bf16 v[112:115], v[184:187], v[192:195], v[112:115]
	v_mfma_f32_16x16x32_bf16 v[100:103], v[176:179], v[200:203], v[100:103]
	v_mfma_f32_16x16x32_bf16 v[96:99], v[184:187], v[200:203], v[96:99]
	v_mfma_f32_16x16x32_bf16 v[84:87], v[176:179], v[208:211], v[84:87]
	v_mfma_f32_16x16x32_bf16 v[80:83], v[184:187], v[208:211], v[80:83]
	v_mfma_f32_16x16x32_bf16 v[68:71], v[176:179], v[216:219], v[68:71]
	v_mfma_f32_16x16x32_bf16 v[64:67], v[184:187], v[216:219], v[64:67]
	s_setprio 0
	s_barrier
	s_add_i32 s23, s23, s48
	v_lshl_add_u64 v[220:221], v[220:221], 0, s[16:17]
	s_mov_b32 m0, s23
	ds_read_b128 v[188:191], v158 offset:49152
	ds_read_b128 v[192:195], v158 offset:50176
	ds_read_b128 v[196:199], v158 offset:51200
	ds_read_b128 v[200:203], v158 offset:52224
	ds_read_b128 v[204:207], v158 offset:53248
	ds_read_b128 v[208:211], v158 offset:54272
	ds_read_b128 v[212:215], v158 offset:55296
	ds_read_b128 v[216:219], v158 offset:56320
	global_load_lds_dwordx4 v[220:221], off
	s_add_i32 m0, s23, 0x2000
	s_add_u32 s40, s40, 0xb0080
	v_lshl_add_u64 v[220:221], v[222:223], 0, s[16:17]
	s_addc_u32 s41, s41, 0
	s_add_i32 s23, s33, s48
	global_load_lds_dwordx4 v[220:221], off
	v_lshl_add_u64 v[220:221], s[40:41], 0, v[132:133]
	s_mov_b32 m0, s23
	s_nop 0
	global_load_lds_dwordx4 v[220:221], off
	v_lshl_add_u64 v[220:221], s[40:41], 0, v[136:137]
	s_add_i32 m0, s23, 0x2000
	s_nop 0
	global_load_lds_dwordx4 v[220:221], off
	v_lshl_add_u64 v[220:221], v[224:225], 0, s[16:17]
	s_mov_b32 m0, s56
	s_nop 0
	global_load_lds_dwordx4 v[220:221], off
	v_lshl_add_u64 v[220:221], v[226:227], 0, s[16:17]
	s_mov_b32 m0, s57
	s_nop 0
	global_load_lds_dwordx4 v[220:221], off
	s_waitcnt vmcnt(8)
	s_waitcnt lgkmcnt(0)
	s_barrier
	s_setprio 1
	s_waitcnt lgkmcnt(0)
	v_mfma_f32_16x16x32_bf16 v[60:63], v[146:149], v[188:191], v[60:63]
	v_mfma_f32_16x16x32_bf16 v[56:59], v[164:167], v[188:191], v[56:59]
	v_mfma_f32_16x16x32_bf16 v[44:47], v[146:149], v[196:199], v[44:47]
	v_mfma_f32_16x16x32_bf16 v[40:43], v[164:167], v[196:199], v[40:43]
	v_mfma_f32_16x16x32_bf16 v[28:31], v[146:149], v[204:207], v[28:31]
	v_mfma_f32_16x16x32_bf16 v[24:27], v[164:167], v[204:207], v[24:27]
	v_mfma_f32_16x16x32_bf16 v[12:15], v[146:149], v[212:215], v[12:15]
	v_mfma_f32_16x16x32_bf16 v[8:11], v[164:167], v[212:215], v[8:11]
	v_mfma_f32_16x16x32_bf16 v[60:63], v[160:163], v[192:195], v[60:63]
	v_mfma_f32_16x16x32_bf16 v[56:59], v[168:171], v[192:195], v[56:59]
	v_mfma_f32_16x16x32_bf16 v[44:47], v[160:163], v[200:203], v[44:47]
	v_mfma_f32_16x16x32_bf16 v[40:43], v[168:171], v[200:203], v[40:43]
	v_mfma_f32_16x16x32_bf16 v[28:31], v[160:163], v[208:211], v[28:31]
	v_mfma_f32_16x16x32_bf16 v[24:27], v[168:171], v[208:211], v[24:27]
	v_mfma_f32_16x16x32_bf16 v[12:15], v[160:163], v[216:219], v[12:15]
	v_mfma_f32_16x16x32_bf16 v[8:11], v[168:171], v[216:219], v[8:11]
	v_mfma_f32_16x16x32_bf16 v[52:55], v[172:175], v[188:191], v[52:55]
	v_mfma_f32_16x16x32_bf16 v[48:51], v[180:183], v[188:191], v[48:51]
	v_mfma_f32_16x16x32_bf16 v[36:39], v[172:175], v[196:199], v[36:39]
	v_mfma_f32_16x16x32_bf16 v[32:35], v[180:183], v[196:199], v[32:35]
	v_mfma_f32_16x16x32_bf16 v[20:23], v[172:175], v[204:207], v[20:23]
	v_mfma_f32_16x16x32_bf16 v[16:19], v[180:183], v[204:207], v[16:19]
	v_mfma_f32_16x16x32_bf16 v[4:7], v[172:175], v[212:215], v[4:7]
	v_mfma_f32_16x16x32_bf16 v[0:3], v[180:183], v[212:215], v[0:3]
	v_mfma_f32_16x16x32_bf16 v[52:55], v[176:179], v[192:195], v[52:55]
	v_mfma_f32_16x16x32_bf16 v[48:51], v[184:187], v[192:195], v[48:51]
	v_mfma_f32_16x16x32_bf16 v[36:39], v[176:179], v[200:203], v[36:39]
	v_mfma_f32_16x16x32_bf16 v[32:35], v[184:187], v[200:203], v[32:35]
	v_mfma_f32_16x16x32_bf16 v[20:23], v[176:179], v[208:211], v[20:23]
	v_mfma_f32_16x16x32_bf16 v[16:19], v[184:187], v[208:211], v[16:19]
	v_mfma_f32_16x16x32_bf16 v[4:7], v[176:179], v[216:219], v[4:7]
	v_mfma_f32_16x16x32_bf16 v[0:3], v[184:187], v[216:219], v[0:3]
	s_setprio 0
	s_barrier
	s_add_i32 s65, s65, 2
	s_add_u32 s38, s38, 0x100
	s_addc_u32 s39, s39, 0
	s_add_u32 s63, s63, 0x100
	s_addc_u32 s64, s64, 0
	s_cmp_gt_u32 s65, 41
	s_cbranch_scc0 .LBB0_1424
	s_and_b64 vcc, exec, s[18:19]
	s_cbranch_vccz .LBB0_1427
	s_barrier
